# P0: bulk bf16 output stores write-through (sc1) so the barrier-1 L2 write-back finds little dirty data; on top of v23
# speedup vs baseline: 1.0059x; 1.0059x over previous
; #define GAS __attribute__((address_space(1)))
; #define LAS __attribute__((address_space(3)))
; #define LDS_WAIT() asm volatile("s_waitcnt lgkmcnt(0)" ::: "memory")
; __device__ __forceinline__ unsigned pk2(float lo, float hi) { return f2bf(lo) | (f2bf(hi) << 16); }
; __device__ __forceinline__ void p0_item_store(const P0Item& I, const float (&wv)[32], LAS float* scr, int lane) {
; #pragma unroll
;     for (int i = 0; i < 8; ++i) { const int kk = 8 * i + (lane >> 3); const float s = I.scale ? I.scale[I.k0 + kk] : 1.f; LAS float* d = scr + kk * 33 + 4 * (lane & 7);
;         d[0] = wv[4 * i] * s; d[1] = wv[4 * i + 1] * s; d[2] = wv[4 * i + 2] * s; d[3] = wv[4 * i + 3] * s; }
;     LDS_WAIT(); asm volatile("" ::: "memory");
;     const int c = lane & 7;
; #pragma unroll
;     for (int j = 0; j < 4; ++j) { const int n = (lane >> 3) + 8 * j; const int ns = I.perm ? rope_perm(n) : n; const LAS float* s = scr + (8 * c) * 33 + ns;
;         v4u o; o.x = pk2(s[0 * 33], s[1 * 33]); o.y = pk2(s[2 * 33], s[3 * 33]); o.z = pk2(s[4 * 33], s[5 * 33]); o.w = pk2(s[6 * 33], s[7 * 33]);
;         *(GAS v4u*)(I.WT + (size_t)(I.out_row0 + n) * I.K + I.k0 + 8 * c) = o; }
;     LDS_WAIT(); asm volatile("" ::: "memory");
; }
.LBB0_47:
	s_waitcnt vmcnt(0)
	v_pk_mul_f32 v[96:97], v[96:97], v[104:105] op_sel_hi:[1,0]
	ds_write2_b32 v139, v96, v97 offset1:1
	v_pk_mul_f32 v[96:97], v[98:99], v[104:105] op_sel_hi:[1,0]
	ds_write2_b32 v140, v96, v97 offset1:1
	s_and_b64 vcc, s[0:1], s[84:85]
	s_waitcnt lgkmcnt(0)
	v_cndmask_b32_e32 v96, v132, v154, vcc
	v_lshl_add_u32 v102, v96, 2, v153
	ds_read2_b32 v[96:97], v102 offset1:33
	s_and_b64 vcc, s[2:3], s[84:85]
	s_lshl_b64 s[8:9], s[86:87], 1
	s_waitcnt lgkmcnt(0)
	v_bfe_u32 v98, v96, 16, 1
	v_add3_u32 v96, v96, v98, s62
	ds_read2_b32 v[98:99], v102 offset0:66 offset1:99
	v_bfe_u32 v100, v97, 16, 1
	v_add3_u32 v97, v97, v100, s62
	ds_read2_b32 v[100:101], v102 offset0:132 offset1:165
	v_lshrrev_b32_e32 v96, 16, v96
	v_and_or_b32 v96, v97, s63, v96
	s_waitcnt lgkmcnt(1)
	v_bfe_u32 v97, v98, 16, 1
	v_add3_u32 v97, v98, v97, s62
	v_bfe_u32 v98, v99, 16, 1
	ds_read2_b32 v[102:103], v102 offset0:198 offset1:231
	v_lshrrev_b32_e32 v97, 16, v97
	v_add3_u32 v98, v99, v98, s62
	v_and_or_b32 v97, v98, s63, v97
	s_waitcnt lgkmcnt(1)
	v_bfe_u32 v98, v100, 16, 1
	v_add3_u32 v98, v100, v98, s62
	v_bfe_u32 v99, v101, 16, 1
	v_lshrrev_b32_e32 v98, 16, v98
	v_add3_u32 v99, v101, v99, s62
	v_and_or_b32 v98, v99, s63, v98
	s_waitcnt lgkmcnt(0)
	v_bfe_u32 v99, v102, 16, 1
	v_add3_u32 v99, v102, v99, s62
	v_bfe_u32 v100, v103, 16, 1
	v_lshrrev_b32_e32 v99, 16, v99
	v_add3_u32 v100, v103, v100, s62
	v_and_or_b32 v99, v100, s63, v99
	v_add_u32_e32 v100, s94, v132
	v_ashrrev_i32_e32 v101, 31, v100
	v_cndmask_b32_e32 v102, v149, v155, vcc
	v_lshlrev_b64 v[100:101], 11, v[100:101]
	v_lshl_add_u32 v104, v102, 2, v153
	v_lshl_add_u64 v[100:101], s[78:79], 0, v[100:101]
	ds_read2_b32 v[102:103], v104 offset1:33
	v_lshl_add_u64 v[100:101], v[100:101], 0, s[8:9]
	v_lshl_add_u64 v[100:101], v[100:101], 0, v[134:135]
	global_store_dwordx4 v[100:101], v[96:99], off sc1
	ds_read2_b32 v[98:99], v104 offset0:66 offset1:99
	ds_read2_b32 v[100:101], v104 offset0:132 offset1:165
	s_waitcnt lgkmcnt(2)
	v_bfe_u32 v96, v102, 16, 1
	v_add3_u32 v96, v102, v96, s62
	v_bfe_u32 v97, v103, 16, 1
	v_lshrrev_b32_e32 v96, 16, v96
	v_add3_u32 v97, v103, v97, s62
	v_and_or_b32 v96, v97, s63, v96
	s_waitcnt lgkmcnt(1)
	v_bfe_u32 v97, v98, 16, 1
	v_add3_u32 v97, v98, v97, s62
	v_bfe_u32 v98, v99, 16, 1
	ds_read2_b32 v[102:103], v104 offset0:198 offset1:231
	v_lshrrev_b32_e32 v97, 16, v97
	v_add3_u32 v98, v99, v98, s62
	v_and_or_b32 v97, v98, s63, v97
	s_waitcnt lgkmcnt(1)
	v_bfe_u32 v98, v100, 16, 1
	v_add3_u32 v98, v100, v98, s62
	v_bfe_u32 v99, v101, 16, 1
	v_lshrrev_b32_e32 v98, 16, v98
	v_add3_u32 v99, v101, v99, s62
	v_and_or_b32 v98, v99, s63, v98
	s_waitcnt lgkmcnt(0)
	v_bfe_u32 v99, v102, 16, 1
	v_add3_u32 v99, v102, v99, s62
	v_bfe_u32 v100, v103, 16, 1
	v_lshrrev_b32_e32 v99, 16, v99
	v_add3_u32 v100, v103, v100, s62
	v_and_or_b32 v99, v100, s63, v99
	v_add_u32_e32 v100, s94, v149
	s_and_b64 vcc, s[4:5], s[84:85]
	v_ashrrev_i32_e32 v101, 31, v100
	v_cndmask_b32_e32 v102, v151, v156, vcc
	v_lshlrev_b64 v[100:101], 11, v[100:101]
	v_lshl_add_u32 v104, v102, 2, v153
	ds_read2_b32 v[102:103], v104 offset1:33
	v_lshl_add_u64 v[100:101], s[78:79], 0, v[100:101]
	v_lshl_add_u64 v[100:101], v[100:101], 0, s[8:9]
	v_lshl_add_u64 v[100:101], v[100:101], 0, v[134:135]
	global_store_dwordx4 v[100:101], v[96:99], off sc1
	ds_read2_b32 v[98:99], v104 offset0:66 offset1:99
	ds_read2_b32 v[100:101], v104 offset0:132 offset1:165
	s_waitcnt lgkmcnt(2)
	v_bfe_u32 v96, v102, 16, 1
	v_add3_u32 v96, v102, v96, s62
	v_bfe_u32 v97, v103, 16, 1
	v_lshrrev_b32_e32 v96, 16, v96
	v_add3_u32 v97, v103, v97, s62
	v_and_or_b32 v96, v97, s63, v96
	s_waitcnt lgkmcnt(1)
	v_bfe_u32 v97, v98, 16, 1
	v_add3_u32 v97, v98, v97, s62
	v_bfe_u32 v98, v99, 16, 1
	ds_read2_b32 v[102:103], v104 offset0:198 offset1:231
	v_lshrrev_b32_e32 v97, 16, v97
	v_add3_u32 v98, v99, v98, s62
	v_and_or_b32 v97, v98, s63, v97
	s_waitcnt lgkmcnt(1)
	v_bfe_u32 v98, v100, 16, 1
	v_add3_u32 v98, v100, v98, s62
	v_bfe_u32 v99, v101, 16, 1
	v_lshrrev_b32_e32 v98, 16, v98
	v_add3_u32 v99, v101, v99, s62
	v_and_or_b32 v98, v99, s63, v98
	s_waitcnt lgkmcnt(0)
	v_bfe_u32 v99, v102, 16, 1
	v_add3_u32 v99, v102, v99, s62
	v_bfe_u32 v100, v103, 16, 1
	v_lshrrev_b32_e32 v99, 16, v99
	v_add3_u32 v100, v103, v100, s62
	v_and_or_b32 v99, v100, s63, v99
	v_add_u32_e32 v100, s94, v151
	s_and_b64 vcc, s[6:7], s[84:85]
	v_ashrrev_i32_e32 v101, 31, v100
	v_cndmask_b32_e32 v102, v152, v157, vcc
	v_lshlrev_b64 v[100:101], 11, v[100:101]
	v_lshl_add_u32 v104, v102, 2, v153
	ds_read2_b32 v[102:103], v104 offset1:33
	v_lshl_add_u64 v[100:101], s[78:79], 0, v[100:101]
	v_lshl_add_u64 v[100:101], v[100:101], 0, s[8:9]
	v_lshl_add_u64 v[100:101], v[100:101], 0, v[134:135]
	global_store_dwordx4 v[100:101], v[96:99], off sc1
	ds_read2_b32 v[98:99], v104 offset0:66 offset1:99
	ds_read2_b32 v[100:101], v104 offset0:132 offset1:165
	s_waitcnt lgkmcnt(2)
	v_bfe_u32 v96, v102, 16, 1
	v_add3_u32 v96, v102, v96, s62
	v_bfe_u32 v97, v103, 16, 1
	v_lshrrev_b32_e32 v96, 16, v96
	v_add3_u32 v97, v103, v97, s62
	v_and_or_b32 v96, v97, s63, v96
	s_waitcnt lgkmcnt(1)
	v_bfe_u32 v97, v98, 16, 1
	v_add3_u32 v97, v98, v97, s62
	v_bfe_u32 v98, v99, 16, 1
	ds_read2_b32 v[102:103], v104 offset0:198 offset1:231
	v_lshrrev_b32_e32 v97, 16, v97
	v_add3_u32 v98, v99, v98, s62
	v_and_or_b32 v97, v98, s63, v97
	s_waitcnt lgkmcnt(1)
	v_bfe_u32 v98, v100, 16, 1
	v_add3_u32 v98, v100, v98, s62
	v_bfe_u32 v99, v101, 16, 1
	v_lshrrev_b32_e32 v98, 16, v98
	v_add3_u32 v99, v101, v99, s62
	v_and_or_b32 v98, v99, s63, v98
	s_waitcnt lgkmcnt(0)
	v_bfe_u32 v99, v102, 16, 1
	v_add3_u32 v99, v102, v99, s62
	v_bfe_u32 v100, v103, 16, 1
	v_lshrrev_b32_e32 v99, 16, v99
	v_add3_u32 v100, v103, v100, s62
	v_and_or_b32 v99, v100, s63, v99
	v_add_u32_e32 v100, s94, v152
	v_ashrrev_i32_e32 v101, 31, v100
	v_lshlrev_b64 v[100:101], 11, v[100:101]
	v_lshl_add_u64 v[100:101], s[78:79], 0, v[100:101]
	v_lshl_add_u64 v[100:101], v[100:101], 0, s[8:9]
	v_lshl_add_u64 v[100:101], v[100:101], 0, v[134:135]
	global_store_dwordx4 v[100:101], v[96:99], off sc1
	s_waitcnt lgkmcnt(0)

; #define GAS __attribute__((address_space(1)))
; #define LAS __attribute__((address_space(3)))
; #define LDS_WAIT() asm volatile("s_waitcnt lgkmcnt(0)" ::: "memory")
; __device__ __forceinline__ unsigned pk2(float lo, float hi) { return f2bf(lo) | (f2bf(hi) << 16); }
; __device__ __forceinline__ void p0_item_store(const P0Item& I, const float (&wv)[32], LAS float* scr, int lane) {
; #pragma unroll
;     for (int i = 0; i < 8; ++i) { const int kk = 8 * i + (lane >> 3); const float s = I.scale ? I.scale[I.k0 + kk] : 1.f; LAS float* d = scr + kk * 33 + 4 * (lane & 7);
;         d[0] = wv[4 * i] * s; d[1] = wv[4 * i + 1] * s; d[2] = wv[4 * i + 2] * s; d[3] = wv[4 * i + 3] * s; }
;     LDS_WAIT(); asm volatile("" ::: "memory");
;     const int c = lane & 7;
; #pragma unroll
;     for (int j = 0; j < 4; ++j) { const int n = (lane >> 3) + 8 * j; const int ns = I.perm ? rope_perm(n) : n; const LAS float* s = scr + (8 * c) * 33 + ns;
;         v4u o; o.x = pk2(s[0 * 33], s[1 * 33]); o.y = pk2(s[2 * 33], s[3 * 33]); o.z = pk2(s[4 * 33], s[5 * 33]); o.w = pk2(s[6 * 33], s[7 * 33]);
;         *(GAS v4u*)(I.WT + (size_t)(I.out_row0 + n) * I.K + I.k0 + 8 * c) = o; }
;     LDS_WAIT(); asm volatile("" ::: "memory");
; }
.LBB0_83:
	v_add_u32_e32 v162, 0xc60, v159
	ds_write2_b32 v162, v142, v143 offset1:1
	v_add_u32_e32 v142, 0xc68, v159
	s_add_i32 s95, s13, s64
	ds_write2_b32 v142, v144, v145 offset1:1
	s_waitcnt vmcnt(0)
	v_pk_mul_f32 v[144:145], v[96:97], v[140:141] op_sel_hi:[1,0]
	v_add_u32_e32 v139, 0x1080, v159
	s_cmpk_lt_i32 s95, 0xa10
	ds_write2_b32 v139, v144, v145 offset1:1
	v_pk_mul_f32 v[144:145], v[98:99], v[140:141] op_sel_hi:[1,0]
	v_add_u32_e32 v140, 0x1088, v159
	s_cselect_b64 s[88:89], -1, 0
	ds_write2_b32 v140, v144, v145 offset1:1
	s_and_b64 vcc, s[0:1], s[84:85]
	s_waitcnt lgkmcnt(0)
	v_cndmask_b32_e32 v138, v132, v154, vcc
	v_lshl_add_u32 v138, v138, 2, v153
	ds_read2_b32 v[144:145], v138 offset1:33
	ds_read2_b32 v[166:167], v138 offset0:66 offset1:99
	ds_read2_b32 v[168:169], v138 offset0:198 offset1:231
	s_add_i32 s83, s34, s83
	s_and_b64 s[14:15], s[2:3], s[84:85]
	s_waitcnt lgkmcnt(2)
	v_bfe_u32 v143, v144, 16, 1
	v_add3_u32 v143, v144, v143, s62
	v_bfe_u32 v144, v145, 16, 1
	v_lshrrev_b32_e32 v143, 16, v143
	v_add3_u32 v144, v145, v144, s62
	v_and_or_b32 v164, v144, s63, v143
	ds_read2_b32 v[144:145], v138 offset0:132 offset1:165
	s_waitcnt lgkmcnt(2)
	v_bfe_u32 v143, v166, 16, 1
	v_add3_u32 v143, v166, v143, s62
	v_bfe_u32 v165, v167, 16, 1
	v_lshrrev_b32_e32 v143, 16, v143
	v_add3_u32 v165, v167, v165, s62
	v_and_or_b32 v165, v165, s63, v143
	s_waitcnt lgkmcnt(0)
	v_bfe_u32 v143, v144, 16, 1
	v_add3_u32 v143, v144, v143, s62
	v_lshrrev_b32_e32 v138, 16, v143
	v_bfe_u32 v143, v145, 16, 1
	v_add3_u32 v143, v145, v143, s62
	v_and_or_b32 v166, v143, s63, v138
	v_bfe_u32 v138, v168, 16, 1
	v_add3_u32 v138, v168, v138, s62
	v_bfe_u32 v143, v169, 16, 1
	v_lshrrev_b32_e32 v138, 16, v138
	v_add3_u32 v143, v169, v143, s62
	v_add_u32_e32 v144, s83, v132
	v_and_or_b32 v167, v143, s63, v138
	v_ashrrev_i32_e32 v145, 31, v144
	v_cndmask_b32_e64 v138, v149, v155, s[14:15]
	s_ashr_i32 s87, s86, 31
	v_lshlrev_b64 v[168:169], 11, v[144:145]
	v_lshl_add_u32 v138, v138, 2, v153
	s_lshl_b64 s[92:93], s[86:87], 1
	ds_read2_b32 v[170:171], v138 offset1:33
	v_lshl_add_u64 v[168:169], s[78:79], 0, v[168:169]
	v_lshl_add_u64 v[168:169], v[168:169], 0, s[92:93]
	v_lshl_add_u64 v[168:169], v[168:169], 0, v[134:135]
	global_store_dwordx4 v[168:169], v[164:167], off sc1
	ds_read2_b32 v[166:167], v138 offset0:66 offset1:99
	s_waitcnt lgkmcnt(1)
	v_bfe_u32 v143, v170, 16, 1
	v_add3_u32 v143, v170, v143, s62
	v_bfe_u32 v145, v171, 16, 1
	ds_read2_b32 v[168:169], v138 offset0:132 offset1:165
	v_lshrrev_b32_e32 v143, 16, v143
	v_add3_u32 v145, v171, v145, s62
	v_and_or_b32 v164, v145, s63, v143
	s_waitcnt lgkmcnt(1)
	v_bfe_u32 v143, v166, 16, 1
	v_add3_u32 v143, v166, v143, s62
	v_bfe_u32 v145, v167, 16, 1
	v_lshrrev_b32_e32 v143, 16, v143
	v_add3_u32 v145, v167, v145, s62
	ds_read2_b32 v[170:171], v138 offset0:198 offset1:231
	v_and_or_b32 v165, v145, s63, v143
	s_waitcnt lgkmcnt(1)
	v_bfe_u32 v143, v168, 16, 1
	v_add3_u32 v143, v168, v143, s62
	v_lshrrev_b32_e32 v138, 16, v143
	v_bfe_u32 v143, v169, 16, 1
	v_add3_u32 v143, v169, v143, s62
	v_and_or_b32 v166, v143, s63, v138
	s_waitcnt lgkmcnt(0)
	v_bfe_u32 v138, v170, 16, 1
	v_add3_u32 v138, v170, v138, s62
	v_bfe_u32 v143, v171, 16, 1
	s_and_b64 s[10:11], s[4:5], s[84:85]
	v_lshrrev_b32_e32 v138, 16, v138
	v_add3_u32 v143, v171, v143, s62
	v_add_u32_e32 v168, 8, v144
	v_and_or_b32 v167, v143, s63, v138
	v_ashrrev_i32_e32 v169, 31, v168
	v_cndmask_b32_e64 v138, v151, v156, s[10:11]
	v_lshlrev_b64 v[168:169], 11, v[168:169]
	v_lshl_add_u32 v138, v138, 2, v153
	ds_read2_b32 v[170:171], v138 offset1:33
	v_lshl_add_u64 v[168:169], s[78:79], 0, v[168:169]
	v_lshl_add_u64 v[168:169], v[168:169], 0, s[92:93]
	v_lshl_add_u64 v[168:169], v[168:169], 0, v[134:135]
	global_store_dwordx4 v[168:169], v[164:167], off sc1
	ds_read2_b32 v[166:167], v138 offset0:66 offset1:99
	s_waitcnt lgkmcnt(1)
	v_bfe_u32 v143, v170, 16, 1
	v_add3_u32 v143, v170, v143, s62
	v_bfe_u32 v145, v171, 16, 1
	ds_read2_b32 v[168:169], v138 offset0:132 offset1:165
	v_lshrrev_b32_e32 v143, 16, v143
	v_add3_u32 v145, v171, v145, s62
	v_and_or_b32 v164, v145, s63, v143
	s_waitcnt lgkmcnt(1)
	v_bfe_u32 v143, v166, 16, 1
	v_add3_u32 v143, v166, v143, s62
	v_bfe_u32 v145, v167, 16, 1
	v_lshrrev_b32_e32 v143, 16, v143
	v_add3_u32 v145, v167, v145, s62
	ds_read2_b32 v[170:171], v138 offset0:198 offset1:231
	v_and_or_b32 v165, v145, s63, v143
	s_waitcnt lgkmcnt(1)
	v_bfe_u32 v143, v168, 16, 1
	v_add3_u32 v143, v168, v143, s62
	v_lshrrev_b32_e32 v138, 16, v143
	v_bfe_u32 v143, v169, 16, 1
	v_add3_u32 v143, v169, v143, s62
	v_and_or_b32 v166, v143, s63, v138
	s_waitcnt lgkmcnt(0)
	v_bfe_u32 v138, v170, 16, 1
	v_add3_u32 v138, v170, v138, s62
	v_bfe_u32 v143, v171, 16, 1
	s_and_b64 vcc, s[6:7], s[84:85]
	v_lshrrev_b32_e32 v138, 16, v138
	v_add3_u32 v143, v171, v143, s62
	v_add_u32_e32 v168, 16, v144
	v_and_or_b32 v167, v143, s63, v138
	v_ashrrev_i32_e32 v169, 31, v168
	v_cndmask_b32_e32 v138, v152, v157, vcc
	v_lshlrev_b64 v[168:169], 11, v[168:169]
	v_lshl_add_u32 v138, v138, 2, v153
	ds_read2_b32 v[170:171], v138 offset1:33
	v_lshl_add_u64 v[168:169], s[78:79], 0, v[168:169]
	v_lshl_add_u64 v[168:169], v[168:169], 0, s[92:93]
	v_lshl_add_u64 v[168:169], v[168:169], 0, v[134:135]
	global_store_dwordx4 v[168:169], v[164:167], off sc1
	ds_read2_b32 v[166:167], v138 offset0:66 offset1:99
	s_waitcnt lgkmcnt(1)
	v_bfe_u32 v143, v170, 16, 1
	v_add3_u32 v143, v170, v143, s62
	v_bfe_u32 v145, v171, 16, 1
	ds_read2_b32 v[168:169], v138 offset0:132 offset1:165
	v_lshrrev_b32_e32 v143, 16, v143
	v_add3_u32 v145, v171, v145, s62
	v_and_or_b32 v164, v145, s63, v143
	s_waitcnt lgkmcnt(1)
	v_bfe_u32 v143, v166, 16, 1
	v_add3_u32 v143, v166, v143, s62
	v_bfe_u32 v145, v167, 16, 1
	v_lshrrev_b32_e32 v143, 16, v143
	v_add3_u32 v145, v167, v145, s62
	ds_read2_b32 v[170:171], v138 offset0:198 offset1:231
	v_and_or_b32 v165, v145, s63, v143
	s_waitcnt lgkmcnt(1)
	v_bfe_u32 v143, v168, 16, 1
	v_add3_u32 v143, v168, v143, s62
	v_lshrrev_b32_e32 v138, 16, v143
	v_bfe_u32 v143, v169, 16, 1
	v_add_u32_e32 v144, 24, v144
	v_add3_u32 v143, v169, v143, s62
	v_ashrrev_i32_e32 v145, 31, v144
	v_and_or_b32 v166, v143, s63, v138
	s_waitcnt lgkmcnt(0)
	v_bfe_u32 v138, v170, 16, 1
	v_lshlrev_b64 v[144:145], 11, v[144:145]
	v_add3_u32 v138, v170, v138, s62
	v_bfe_u32 v143, v171, 16, 1
	v_lshl_add_u64 v[144:145], s[78:79], 0, v[144:145]
	v_lshrrev_b32_e32 v138, 16, v138
	v_add3_u32 v143, v171, v143, s62
	v_lshl_add_u64 v[144:145], v[144:145], 0, s[92:93]
	v_and_or_b32 v167, v143, s63, v138
	v_lshl_add_u64 v[144:145], v[144:145], 0, v[134:135]
	global_store_dwordx4 v[144:145], v[164:167], off sc1
	s_waitcnt lgkmcnt(0)
	s_cmpk_gt_i32 s95, 0xa0f
	s_cbranch_scc1 .LBB0_98
; __device__ __forceinline__ void win_block(int nb, int& src0, bool& perm) {
;     const int n = nb * 32; perm = false;
;     if (n < 2560) { src0 = n; }
;     else if (n < 3584) { const int j = n - 2560; src0 = 2592 + j; perm = ((j & 63) == 0); }
;     else if (n < 3840) { const int j = n - 3584; src0 = 3616 + j; perm = ((j & 63) == 0); }
;     else if (n < 4096) { src0 = 3872 + (n - 3840); }
;     else if (n < 5120) { src0 = 4128 + (n - 4096); }
;     else { src0 = 2560 + (n - 5120); }
; }
	s_mul_hi_i32 s10, s95, 0xcb8727c1
	s_add_i32 s10, s10, s95
	s_lshr_b32 s11, s10, 31
	s_ashr_i32 s10, s10, 7
	s_add_i32 s11, s10, s11
	s_mul_i32 s10, s11, 0xa1
	s_sub_i32 s83, s95, s10
	s_lshl_b32 s94, s83, 5
	s_mov_b64 s[84:85], 0
	s_cmpk_lt_i32 s83, 0x50
	s_mov_b32 s10, s94
	s_cbranch_scc1 .LBB0_96
	s_cmpk_gt_u32 s83, 0x6f
	s_mov_b64 s[14:15], -1
	s_cbranch_scc0 .LBB0_94
	s_cmpk_gt_u32 s83, 0x77
	s_mov_b64 s[84:85], -1
	s_cbranch_scc0 .LBB0_92
	s_cmpk_gt_u32 s83, 0x7f
	s_cbranch_scc0 .LBB0_89
	s_add_i32 s10, s94, 32
	s_cmpk_lt_u32 s83, 0xa0
	s_cselect_b32 s10, s10, 0xa00
	s_mov_b64 s[14:15], 0

; #define GAS __attribute__((address_space(1)))
; #define LAS __attribute__((address_space(3)))
; #define LDS_WAIT() asm volatile("s_waitcnt lgkmcnt(0)" ::: "memory")
; __device__ __forceinline__ unsigned pk2(float lo, float hi) { return f2bf(lo) | (f2bf(hi) << 16); }
; __device__ __forceinline__ void p0_item_store(const P0Item& I, const float (&wv)[32], LAS float* scr, int lane) {
; #pragma unroll
;     for (int i = 0; i < 8; ++i) { const int kk = 8 * i + (lane >> 3); const float s = I.scale ? I.scale[I.k0 + kk] : 1.f; LAS float* d = scr + kk * 33 + 4 * (lane & 7);
;         d[0] = wv[4 * i] * s; d[1] = wv[4 * i + 1] * s; d[2] = wv[4 * i + 2] * s; d[3] = wv[4 * i + 3] * s; }
;     LDS_WAIT(); asm volatile("" ::: "memory");
;     const int c = lane & 7;
; #pragma unroll
;     for (int j = 0; j < 4; ++j) { const int n = (lane >> 3) + 8 * j; const int ns = I.perm ? rope_perm(n) : n; const LAS float* s = scr + (8 * c) * 33 + ns;
;         v4u o; o.x = pk2(s[0 * 33], s[1 * 33]); o.y = pk2(s[2 * 33], s[3 * 33]); o.z = pk2(s[4 * 33], s[5 * 33]); o.w = pk2(s[6 * 33], s[7 * 33]);
;         *(GAS v4u*)(I.WT + (size_t)(I.out_row0 + n) * I.K + I.k0 + 8 * c) = o; }
;     LDS_WAIT(); asm volatile("" ::: "memory");
; }
.LBB0_111:
	s_waitcnt vmcnt(0)
	v_pk_mul_f32 v[144:145], v[88:89], v[138:139] op_sel_hi:[1,0]
	ds_write2_b32 v139, v144, v145 offset1:1
	v_pk_mul_f32 v[144:145], v[90:91], v[138:139] op_sel_hi:[1,0]
	ds_write2_b32 v140, v144, v145 offset1:1
	s_and_b64 vcc, s[0:1], s[80:81]
	s_waitcnt lgkmcnt(0)
	v_cndmask_b32_e32 v138, v132, v154, vcc
	v_lshl_add_u32 v138, v138, 2, v153
	ds_read2_b32 v[144:145], v138 offset1:33
	s_lshl_b64 s[10:11], s[82:83], 1
	s_and_b64 vcc, s[2:3], s[80:81]
	s_waitcnt lgkmcnt(0)
	v_bfe_u32 v143, v144, 16, 1
	v_add3_u32 v143, v144, v143, s62
	v_bfe_u32 v144, v145, 16, 1
	v_lshrrev_b32_e32 v143, 16, v143
	v_add3_u32 v144, v145, v144, s62
	v_and_or_b32 v164, v144, s63, v143
	ds_read2_b32 v[144:145], v138 offset0:66 offset1:99
	s_waitcnt lgkmcnt(0)
	v_bfe_u32 v143, v144, 16, 1
	v_add3_u32 v143, v144, v143, s62
	v_bfe_u32 v144, v145, 16, 1
	v_lshrrev_b32_e32 v143, 16, v143
	v_add3_u32 v144, v145, v144, s62
	v_and_or_b32 v165, v144, s63, v143
	ds_read2_b32 v[144:145], v138 offset0:132 offset1:165
	s_waitcnt lgkmcnt(0)
	v_bfe_u32 v143, v144, 16, 1
	v_add3_u32 v143, v144, v143, s62
	v_bfe_u32 v144, v145, 16, 1
	v_lshrrev_b32_e32 v143, 16, v143
	v_add3_u32 v144, v145, v144, s62
	v_and_or_b32 v166, v144, s63, v143
	ds_read2_b32 v[144:145], v138 offset0:198 offset1:231
	s_waitcnt lgkmcnt(0)
	v_bfe_u32 v138, v144, 16, 1
	v_add3_u32 v138, v144, v138, s62
	v_bfe_u32 v143, v145, 16, 1
	v_add_u32_e32 v144, s65, v132
	v_add3_u32 v143, v145, v143, s62
	v_ashrrev_i32_e32 v145, 31, v144
	v_lshlrev_b64 v[144:145], 11, v[144:145]
	v_lshrrev_b32_e32 v138, 16, v138
	v_lshl_add_u64 v[144:145], s[78:79], 0, v[144:145]
	v_and_or_b32 v167, v143, s63, v138
	v_lshl_add_u64 v[144:145], v[144:145], 0, s[10:11]
	v_cndmask_b32_e32 v138, v149, v155, vcc
	v_lshl_add_u64 v[144:145], v[144:145], 0, v[134:135]
	v_lshl_add_u32 v138, v138, 2, v153
	global_store_dwordx4 v[144:145], v[164:167], off sc1
	ds_read2_b32 v[144:145], v138 offset1:33
	s_and_b64 vcc, s[4:5], s[80:81]
	s_waitcnt lgkmcnt(0)
	v_bfe_u32 v143, v144, 16, 1
	v_add3_u32 v143, v144, v143, s62
	v_bfe_u32 v144, v145, 16, 1
	v_lshrrev_b32_e32 v143, 16, v143
	v_add3_u32 v144, v145, v144, s62
	v_and_or_b32 v164, v144, s63, v143
	ds_read2_b32 v[144:145], v138 offset0:66 offset1:99
	s_waitcnt lgkmcnt(0)
	v_bfe_u32 v143, v144, 16, 1
	v_add3_u32 v143, v144, v143, s62
	v_bfe_u32 v144, v145, 16, 1
	v_lshrrev_b32_e32 v143, 16, v143
	v_add3_u32 v144, v145, v144, s62
	v_and_or_b32 v165, v144, s63, v143
	ds_read2_b32 v[144:145], v138 offset0:132 offset1:165
	s_waitcnt lgkmcnt(0)
	v_bfe_u32 v143, v144, 16, 1
	v_add3_u32 v143, v144, v143, s62
	v_bfe_u32 v144, v145, 16, 1
	v_lshrrev_b32_e32 v143, 16, v143
	v_add3_u32 v144, v145, v144, s62
	v_and_or_b32 v166, v144, s63, v143
	ds_read2_b32 v[144:145], v138 offset0:198 offset1:231
	s_waitcnt lgkmcnt(0)
	v_bfe_u32 v138, v144, 16, 1
	v_add3_u32 v138, v144, v138, s62
	v_bfe_u32 v143, v145, 16, 1
	v_add_u32_e32 v144, s65, v149
	v_add3_u32 v143, v145, v143, s62
	v_ashrrev_i32_e32 v145, 31, v144
	v_lshlrev_b64 v[144:145], 11, v[144:145]
	v_lshrrev_b32_e32 v138, 16, v138
	v_lshl_add_u64 v[144:145], s[78:79], 0, v[144:145]
	v_and_or_b32 v167, v143, s63, v138
	v_lshl_add_u64 v[144:145], v[144:145], 0, s[10:11]
	v_cndmask_b32_e32 v138, v151, v156, vcc
	v_lshl_add_u64 v[144:145], v[144:145], 0, v[134:135]
	v_lshl_add_u32 v138, v138, 2, v153
	global_store_dwordx4 v[144:145], v[164:167], off sc1
	ds_read2_b32 v[144:145], v138 offset1:33
	s_and_b64 vcc, s[6:7], s[80:81]
	s_waitcnt lgkmcnt(0)
	v_bfe_u32 v143, v144, 16, 1
	v_add3_u32 v143, v144, v143, s62
	v_bfe_u32 v144, v145, 16, 1
	v_lshrrev_b32_e32 v143, 16, v143
	v_add3_u32 v144, v145, v144, s62
	v_and_or_b32 v164, v144, s63, v143
	ds_read2_b32 v[144:145], v138 offset0:66 offset1:99
	s_waitcnt lgkmcnt(0)
	v_bfe_u32 v143, v144, 16, 1
	v_add3_u32 v143, v144, v143, s62
	v_bfe_u32 v144, v145, 16, 1
	v_lshrrev_b32_e32 v143, 16, v143
	v_add3_u32 v144, v145, v144, s62
	v_and_or_b32 v165, v144, s63, v143
	ds_read2_b32 v[144:145], v138 offset0:132 offset1:165
	s_waitcnt lgkmcnt(0)
	v_bfe_u32 v143, v144, 16, 1
	v_add3_u32 v143, v144, v143, s62
	v_bfe_u32 v144, v145, 16, 1
	v_lshrrev_b32_e32 v143, 16, v143
	v_add3_u32 v144, v145, v144, s62
	v_and_or_b32 v166, v144, s63, v143
	ds_read2_b32 v[144:145], v138 offset0:198 offset1:231
	s_waitcnt lgkmcnt(0)
	v_bfe_u32 v138, v144, 16, 1
	v_add3_u32 v138, v144, v138, s62
	v_bfe_u32 v143, v145, 16, 1
	v_add_u32_e32 v144, s65, v151
	v_add3_u32 v143, v145, v143, s62
	v_ashrrev_i32_e32 v145, 31, v144
	v_lshlrev_b64 v[144:145], 11, v[144:145]
	v_lshrrev_b32_e32 v138, 16, v138
	v_lshl_add_u64 v[144:145], s[78:79], 0, v[144:145]
	v_and_or_b32 v167, v143, s63, v138
	v_lshl_add_u64 v[144:145], v[144:145], 0, s[10:11]
	v_cndmask_b32_e32 v138, v152, v157, vcc
	v_lshl_add_u64 v[144:145], v[144:145], 0, v[134:135]
	v_lshl_add_u32 v138, v138, 2, v153
	global_store_dwordx4 v[144:145], v[164:167], off sc1
	ds_read2_b32 v[144:145], v138 offset1:33
	s_waitcnt lgkmcnt(0)
	v_bfe_u32 v143, v144, 16, 1
	v_add3_u32 v143, v144, v143, s62
	v_bfe_u32 v144, v145, 16, 1
	v_lshrrev_b32_e32 v143, 16, v143
	v_add3_u32 v144, v145, v144, s62
	v_and_or_b32 v164, v144, s63, v143
	ds_read2_b32 v[144:145], v138 offset0:66 offset1:99
	s_waitcnt lgkmcnt(0)
	v_bfe_u32 v143, v144, 16, 1
	v_add3_u32 v143, v144, v143, s62
	v_bfe_u32 v144, v145, 16, 1
	v_lshrrev_b32_e32 v143, 16, v143
	v_add3_u32 v144, v145, v144, s62
	v_and_or_b32 v165, v144, s63, v143
	ds_read2_b32 v[144:145], v138 offset0:132 offset1:165
	s_waitcnt lgkmcnt(0)
	v_bfe_u32 v143, v144, 16, 1
	v_add3_u32 v143, v144, v143, s62
	v_bfe_u32 v144, v145, 16, 1
	v_lshrrev_b32_e32 v143, 16, v143
	v_add3_u32 v144, v145, v144, s62
	v_and_or_b32 v166, v144, s63, v143
	ds_read2_b32 v[144:145], v138 offset0:198 offset1:231
	s_waitcnt lgkmcnt(0)
	v_bfe_u32 v138, v144, 16, 1
	v_add3_u32 v138, v144, v138, s62
	v_bfe_u32 v143, v145, 16, 1
	v_add_u32_e32 v144, s65, v152
	v_add3_u32 v143, v145, v143, s62
	v_ashrrev_i32_e32 v145, 31, v144
	v_lshlrev_b64 v[144:145], 11, v[144:145]
	v_lshl_add_u64 v[144:145], s[78:79], 0, v[144:145]
	v_lshrrev_b32_e32 v138, 16, v138
	v_lshl_add_u64 v[144:145], v[144:145], 0, s[10:11]
	v_and_or_b32 v167, v143, s63, v138
	v_lshl_add_u64 v[144:145], v[144:145], 0, v[134:135]
	global_store_dwordx4 v[144:145], v[164:167], off sc1
	s_waitcnt lgkmcnt(0)
	s_andn2_b64 vcc, exec, s[88:89]
	s_cbranch_vccnz .LBB0_48

; #define GAS __attribute__((address_space(1)))
; __device__ __forceinline__ void p0_prologue(Frame& F, const Ptrs& P) {
;     ...
;     {
;         f32x4 vb[4][4];
; #pragma unroll
;         for (int r = 0; r < 4; ++r) { const GAS f32x4* xr = (const GAS f32x4*)(P.x + (size_t)(gw + (4 + r) * NGW) * DM) + lane;
; #pragma unroll
;             for (int j = 0; j < 4; ++j) vb[r][j] = xr[64 * j]; }
;         P0_XROWS(va, gw);
;         P0_XROWS(vb, gw + 4 * NGW);
.LBB0_131:
	s_add_u32 s14, s96, 0x180000
	s_addc_u32 s15, s97, 0
	s_add_u32 s20, s96, 0x1400000
	v_readlane_b32 s0, v252, 2
	s_addc_u32 s21, s97, 0
	s_lshl_b32 s0, s0, 5
	s_add_i32 s6, s70, s0
	s_ashr_i32 s7, s6, 31
	s_lshl_b64 s[0:1], s[6:7], 12
	s_add_u32 s0, s16, s0
	s_addc_u32 s1, s17, s1
	s_add_i32 s8, s6, s33
	s_ashr_i32 s9, s8, 31
	v_lshl_add_u64 v[64:65], s[0:1], 0, v[130:131]
	s_lshl_b64 s[0:1], s[8:9], 12
	s_add_u32 s0, s16, s0
	s_addc_u32 s1, s17, s1
	global_load_dwordx4 v[124:127], v[64:65], off
	global_load_dwordx4 v[120:123], v[64:65], off offset:1024
	global_load_dwordx4 v[116:119], v[64:65], off offset:2048
	global_load_dwordx4 v[112:115], v[64:65], off offset:3072
	v_lshl_add_u64 v[64:65], s[0:1], 0, v[130:131]
	s_add_i32 s0, s8, s33
	s_ashr_i32 s1, s0, 31
	s_lshl_b64 s[2:3], s[0:1], 12
	s_add_u32 s2, s16, s2
	s_addc_u32 s3, s17, s3
	s_add_i32 s0, s0, s33
	s_ashr_i32 s1, s0, 31
	s_lshl_b64 s[0:1], s[0:1], 12
	s_add_u32 s0, s16, s0
	global_load_dwordx4 v[108:111], v[64:65], off
	global_load_dwordx4 v[104:107], v[64:65], off offset:1024
	global_load_dwordx4 v[100:103], v[64:65], off offset:2048
	global_load_dwordx4 v[96:99], v[64:65], off offset:3072
	v_lshl_add_u64 v[64:65], s[2:3], 0, v[130:131]
	s_addc_u32 s1, s17, s1
	global_load_dwordx4 v[92:95], v[64:65], off
	global_load_dwordx4 v[88:91], v[64:65], off offset:1024
	global_load_dwordx4 v[84:87], v[64:65], off offset:2048
	global_load_dwordx4 v[80:83], v[64:65], off offset:3072
	v_lshl_add_u64 v[64:65], s[0:1], 0, v[130:131]
	global_load_dwordx4 v[76:79], v[64:65], off
	global_load_dwordx4 v[72:75], v[64:65], off offset:1024
	global_load_dwordx4 v[68:71], v[64:65], off offset:2048
	s_nop 0
	global_load_dwordx4 v[64:67], v[64:65], off offset:3072
	s_waitcnt vmcnt(31)
	v_mul_f32_e32 v132, v61, v61
	v_mul_f32_e32 v133, v63, v63
	v_fmac_f32_e32 v132, v60, v60
	v_fmac_f32_e32 v133, v62, v62
	v_add_f32_e32 v132, v132, v133
	s_waitcnt vmcnt(30)
	v_mul_f32_e32 v133, v57, v57
	v_mul_f32_e32 v135, v59, v59
	v_fmac_f32_e32 v133, v56, v56
	v_fmac_f32_e32 v135, v58, v58
	v_add_f32_e32 v133, v133, v135
	v_mbcnt_lo_u32_b32 v130, -1, 0
	v_add_f32_e32 v132, v132, v133
	s_waitcnt vmcnt(29)
	v_mul_f32_e32 v133, v53, v53
	v_mul_f32_e32 v135, v55, v55
	v_mbcnt_hi_u32_b32 v134, -1, v130
	v_fmac_f32_e32 v133, v52, v52
	v_fmac_f32_e32 v135, v54, v54
	v_and_b32_e32 v130, 64, v134
	v_add_f32_e32 v133, v133, v135
	v_add_u32_e32 v136, 64, v130
	v_xor_b32_e32 v130, 1, v134
	v_add_f32_e32 v132, v132, v133
	s_waitcnt vmcnt(28)
	v_mul_f32_e32 v133, v49, v49
	v_mul_f32_e32 v135, v51, v51
	v_cmp_lt_i32_e32 vcc, v130, v136
	v_fmac_f32_e32 v133, v48, v48
	v_fmac_f32_e32 v135, v50, v50
	v_cndmask_b32_e32 v130, v134, v130, vcc
	v_add_f32_e32 v133, v133, v135
	v_lshlrev_b32_e32 v130, 2, v130
	v_add_f32_e32 v132, v132, v133
	ds_bpermute_b32 v133, v130, v132
	v_xor_b32_e32 v131, 2, v134
	v_cmp_lt_i32_e32 vcc, v131, v136
	v_xor_b32_e32 v135, 4, v134
	v_bfe_u32 v140, v60, 16, 1
	v_cndmask_b32_e32 v131, v134, v131, vcc
	v_lshlrev_b32_e32 v131, 2, v131
	s_waitcnt lgkmcnt(0)
	v_add_f32_e32 v133, v132, v133
	ds_bpermute_b32 v137, v131, v133
	v_cmp_lt_i32_e32 vcc, v135, v136
	s_movk_i32 s16, 0x7fff
	v_add3_u32 v60, v60, v140, s16
	v_cndmask_b32_e32 v132, v134, v135, vcc
	v_lshlrev_b32_e32 v132, 2, v132
	s_waitcnt lgkmcnt(0)
	v_add_f32_e32 v137, v133, v137
	ds_bpermute_b32 v138, v132, v137
	v_xor_b32_e32 v135, 8, v134
	v_cmp_lt_i32_e32 vcc, v135, v136
	v_bfe_u32 v140, v61, 16, 1
	v_lshrrev_b32_e32 v60, 16, v60
	v_cndmask_b32_e32 v133, v134, v135, vcc
	v_lshlrev_b32_e32 v133, 2, v133
	s_waitcnt lgkmcnt(0)
	v_add_f32_e32 v137, v137, v138
	ds_bpermute_b32 v138, v133, v137
	v_xor_b32_e32 v135, 16, v134
	v_cmp_lt_i32_e32 vcc, v135, v136
	v_add3_u32 v61, v61, v140, s16
	s_mov_b32 s17, 0xffff0000
	v_cndmask_b32_e32 v135, v134, v135, vcc
	v_lshlrev_b32_e32 v135, 2, v135
	s_waitcnt lgkmcnt(0)
	v_add_f32_e32 v137, v137, v138
	ds_bpermute_b32 v138, v135, v137
	s_lshl_b64 s[4:5], s[70:71], 11
	v_and_or_b32 v60, v61, s17, v60
	v_bfe_u32 v61, v62, 16, 1
	v_xor_b32_e32 v139, 32, v134
	s_add_u32 s2, s20, s4
	v_add3_u32 v61, v62, v61, s16
	v_bfe_u32 v62, v63, 16, 1
	v_cmp_lt_i32_e32 vcc, v139, v136
	s_addc_u32 s3, s21, s5
	v_lshrrev_b32_e32 v61, 16, v61
	v_add3_u32 v62, v63, v62, s16
	v_cndmask_b32_e32 v134, v134, v139, vcc
	s_waitcnt lgkmcnt(0)
	v_add_f32_e32 v136, v137, v138
	v_lshl_add_u64 v[138:139], v[128:129], 3, s[2:3]
	v_and_or_b32 v61, v62, s17, v61
	global_store_dwordx2 v[138:139], v[60:61], off sc1
	v_bfe_u32 v60, v56, 16, 1
	v_add3_u32 v56, v56, v60, s16
	v_bfe_u32 v60, v57, 16, 1
	v_lshrrev_b32_e32 v56, 16, v56
	v_add3_u32 v57, v57, v60, s16
	v_and_or_b32 v56, v57, s17, v56
	v_bfe_u32 v57, v58, 16, 1
	v_add3_u32 v57, v58, v57, s16
	v_bfe_u32 v58, v59, 16, 1
	v_lshrrev_b32_e32 v57, 16, v57
	v_add3_u32 v58, v59, v58, s16
	v_and_or_b32 v57, v58, s17, v57
	global_store_dwordx2 v[138:139], v[56:57], off offset:512 sc1
	v_bfe_u32 v56, v52, 16, 1
	v_add3_u32 v52, v52, v56, s16
	v_bfe_u32 v56, v53, 16, 1
	v_lshrrev_b32_e32 v52, 16, v52
	v_add3_u32 v53, v53, v56, s16
	v_and_or_b32 v52, v53, s17, v52
	v_bfe_u32 v53, v54, 16, 1
	v_add3_u32 v53, v54, v53, s16
	v_bfe_u32 v54, v55, 16, 1
	v_lshrrev_b32_e32 v53, 16, v53
	v_add3_u32 v54, v55, v54, s16
	v_and_or_b32 v53, v54, s17, v53
	global_store_dwordx2 v[138:139], v[52:53], off offset:1024 sc1
	v_bfe_u32 v52, v48, 16, 1
	v_lshlrev_b32_e32 v134, 2, v134
	v_add3_u32 v48, v48, v52, s16
	v_bfe_u32 v52, v49, 16, 1
	ds_bpermute_b32 v137, v134, v136
	v_lshrrev_b32_e32 v48, 16, v48
	v_add3_u32 v49, v49, v52, s16
	v_and_or_b32 v48, v49, s17, v48
	v_bfe_u32 v49, v50, 16, 1
	v_add3_u32 v49, v50, v49, s16
	v_bfe_u32 v50, v51, 16, 1
	v_lshrrev_b32_e32 v49, 16, v49
	v_add3_u32 v50, v51, v50, s16
	v_cmp_eq_u32_e64 s[0:1], 0, v128
	v_and_or_b32 v49, v50, s17, v49
	global_store_dwordx2 v[138:139], v[48:49], off offset:1536 sc1
	s_and_saveexec_b64 s[10:11], s[0:1]
	s_cbranch_execz .LBB0_133
	s_waitcnt lgkmcnt(0)
	v_add_f32_e32 v48, v136, v137
	v_mov_b32_e32 v49, 0x358637bd
	v_fmac_f32_e32 v49, 0x3a800000, v48
	s_mov_b32 s2, 0xf800000
	v_mul_f32_e32 v48, 0x4f800000, v49
	v_cmp_gt_f32_e32 vcc, s2, v49
	s_nop 1
	v_cndmask_b32_e32 v48, v49, v48, vcc
	v_sqrt_f32_e32 v49, v48
	s_nop 0
	v_add_u32_e32 v50, -1, v49
	v_fma_f32 v51, -v50, v49, v48
	v_cmp_ge_f32_e64 s[2:3], 0, v51
	v_add_u32_e32 v51, 1, v49
	s_nop 0
	v_cndmask_b32_e64 v50, v49, v50, s[2:3]
	v_fma_f32 v49, -v51, v49, v48
	v_cmp_lt_f32_e64 s[2:3], 0, v49
	s_nop 1
	v_cndmask_b32_e64 v49, v50, v51, s[2:3]
	v_mul_f32_e32 v50, 0x37800000, v49
	v_cndmask_b32_e32 v49, v49, v50, vcc
	v_mov_b32_e32 v50, 0x260
	v_cmp_class_f32_e32 vcc, v48, v50
	s_nop 1
	v_cndmask_b32_e32 v48, v49, v48, vcc
	v_div_scale_f32 v49, s[2:3], v48, v48, 1.0
	v_rcp_f32_e32 v50, v49
	s_lshl_b64 s[2:3], s[70:71], 2
	s_add_u32 s2, s14, s2
	s_addc_u32 s3, s15, s3
	v_fma_f32 v51, -v49, v50, 1.0
	v_fmac_f32_e32 v50, v51, v50
	v_div_scale_f32 v51, vcc, 1.0, v48, 1.0
	v_mul_f32_e32 v52, v51, v50
	v_fma_f32 v53, -v49, v52, v51
	v_fmac_f32_e32 v52, v53, v50
	v_fma_f32 v49, -v49, v52, v51
	v_div_fmas_f32 v49, v49, v50, v52
	v_div_fixup_f32 v48, v49, v48, 1.0
	v_mov_b32_e32 v49, 0
	global_store_dword v49, v48, s[2:3]
.LBB0_133:
	s_or_b64 exec, exec, s[10:11]
	s_waitcnt vmcnt(31)
	v_mul_f32_e32 v48, v45, v45
	v_mul_f32_e32 v49, v47, v47
	v_fmac_f32_e32 v48, v44, v44
	v_fmac_f32_e32 v49, v46, v46
	v_add_f32_e32 v48, v48, v49
	s_waitcnt vmcnt(30)
	v_mul_f32_e32 v49, v41, v41
	v_mul_f32_e32 v50, v43, v43
	v_fmac_f32_e32 v49, v40, v40
	v_fmac_f32_e32 v50, v42, v42
	v_add_f32_e32 v49, v49, v50
	v_add_f32_e32 v48, v48, v49
	s_waitcnt vmcnt(29)
	v_mul_f32_e32 v49, v37, v37
	v_mul_f32_e32 v50, v39, v39
	v_fmac_f32_e32 v49, v36, v36
	v_fmac_f32_e32 v50, v38, v38
	v_add_f32_e32 v49, v49, v50
	v_add_f32_e32 v48, v48, v49
	s_waitcnt vmcnt(28)
	v_mul_f32_e32 v49, v33, v33
	v_mul_f32_e32 v50, v35, v35
	v_fmac_f32_e32 v49, v32, v32
	v_fmac_f32_e32 v50, v34, v34
	v_add_f32_e32 v49, v49, v50
	v_add_f32_e32 v48, v48, v49
	ds_bpermute_b32 v49, v130, v48
	v_bfe_u32 v52, v44, 16, 1
	v_add3_u32 v44, v44, v52, s16
	v_bfe_u32 v52, v45, 16, 1
	v_lshrrev_b32_e32 v44, 16, v44
	s_waitcnt lgkmcnt(0)
	v_add_f32_e32 v48, v48, v49
	ds_bpermute_b32 v49, v131, v48
	v_add3_u32 v45, v45, v52, s16
	s_lshl_b64 s[2:3], s[76:77], 11
	v_and_or_b32 v44, v45, s17, v44
	v_bfe_u32 v45, v46, 16, 1
	s_waitcnt lgkmcnt(0)
	v_add_f32_e32 v48, v48, v49
	s_add_u32 s2, s20, s2
	v_add3_u32 v45, v46, v45, s16
	v_bfe_u32 v46, v47, 16, 1
	ds_bpermute_b32 v49, v132, v48
	s_addc_u32 s3, s21, s3
	v_lshrrev_b32_e32 v45, 16, v45
	v_add3_u32 v46, v47, v46, s16
	v_lshl_add_u64 v[50:51], v[128:129], 3, s[2:3]
	v_and_or_b32 v45, v46, s17, v45
	global_store_dwordx2 v[50:51], v[44:45], off sc1
	v_bfe_u32 v44, v40, 16, 1
	v_add3_u32 v40, v40, v44, s16
	v_bfe_u32 v44, v41, 16, 1
	v_lshrrev_b32_e32 v40, 16, v40
	v_add3_u32 v41, v41, v44, s16
	s_waitcnt lgkmcnt(0)
	v_add_f32_e32 v48, v48, v49
	v_and_or_b32 v40, v41, s17, v40
	v_bfe_u32 v41, v42, 16, 1
	ds_bpermute_b32 v49, v133, v48
	v_add3_u32 v41, v42, v41, s16
	v_bfe_u32 v42, v43, 16, 1
	v_lshrrev_b32_e32 v41, 16, v41
	v_add3_u32 v42, v43, v42, s16
	v_and_or_b32 v41, v42, s17, v41
	global_store_dwordx2 v[50:51], v[40:41], off offset:512 sc1
	v_bfe_u32 v40, v36, 16, 1
	v_add3_u32 v36, v36, v40, s16
	v_bfe_u32 v40, v37, 16, 1
	s_waitcnt lgkmcnt(0)
	v_add_f32_e32 v48, v48, v49
	v_lshrrev_b32_e32 v36, 16, v36
	v_add3_u32 v37, v37, v40, s16
	ds_bpermute_b32 v49, v135, v48
	v_and_or_b32 v36, v37, s17, v36
	v_bfe_u32 v37, v38, 16, 1
	v_add3_u32 v37, v38, v37, s16
	v_bfe_u32 v38, v39, 16, 1
	v_lshrrev_b32_e32 v37, 16, v37
	v_add3_u32 v38, v39, v38, s16
	v_and_or_b32 v37, v38, s17, v37
	global_store_dwordx2 v[50:51], v[36:37], off offset:1024 sc1
	v_bfe_u32 v36, v32, 16, 1
	s_waitcnt lgkmcnt(0)
	v_add_f32_e32 v48, v48, v49
	v_add3_u32 v32, v32, v36, s16
	v_bfe_u32 v36, v33, 16, 1
	ds_bpermute_b32 v49, v134, v48
	v_lshrrev_b32_e32 v32, 16, v32
	v_add3_u32 v33, v33, v36, s16
	v_and_or_b32 v32, v33, s17, v32
	v_bfe_u32 v33, v34, 16, 1
	v_add3_u32 v33, v34, v33, s16
	v_bfe_u32 v34, v35, 16, 1
	v_lshrrev_b32_e32 v33, 16, v33
	v_add3_u32 v34, v35, v34, s16
	v_and_or_b32 v33, v34, s17, v33
	global_store_dwordx2 v[50:51], v[32:33], off offset:1536 sc1
	s_and_saveexec_b64 s[10:11], s[0:1]
	s_cbranch_execz .LBB0_135
	s_waitcnt lgkmcnt(0)
	v_add_f32_e32 v32, v48, v49
	v_mov_b32_e32 v33, 0x358637bd
	v_fmac_f32_e32 v33, 0x3a800000, v32
	s_mov_b32 s2, 0xf800000
	v_mul_f32_e32 v32, 0x4f800000, v33
	v_cmp_gt_f32_e32 vcc, s2, v33
	s_nop 1
	v_cndmask_b32_e32 v32, v33, v32, vcc
	v_sqrt_f32_e32 v33, v32
	s_nop 0
	v_add_u32_e32 v34, -1, v33
	v_fma_f32 v35, -v34, v33, v32
	v_cmp_ge_f32_e64 s[2:3], 0, v35
	v_add_u32_e32 v35, 1, v33
	s_nop 0
	v_cndmask_b32_e64 v34, v33, v34, s[2:3]
	v_fma_f32 v33, -v35, v33, v32
	v_cmp_lt_f32_e64 s[2:3], 0, v33
	s_nop 1
	v_cndmask_b32_e64 v33, v34, v35, s[2:3]
	v_mul_f32_e32 v34, 0x37800000, v33
	v_cndmask_b32_e32 v33, v33, v34, vcc
	v_mov_b32_e32 v34, 0x260
	v_cmp_class_f32_e32 vcc, v32, v34
	s_nop 1
	v_cndmask_b32_e32 v32, v33, v32, vcc
	v_div_scale_f32 v33, s[2:3], v32, v32, 1.0
	v_rcp_f32_e32 v34, v33
	s_lshl_b64 s[2:3], s[76:77], 2
	s_add_u32 s2, s14, s2
	s_addc_u32 s3, s15, s3
	v_fma_f32 v35, -v33, v34, 1.0
	v_fmac_f32_e32 v34, v35, v34
	v_div_scale_f32 v35, vcc, 1.0, v32, 1.0
	v_mul_f32_e32 v36, v35, v34
	v_fma_f32 v37, -v33, v36, v35
	v_fmac_f32_e32 v36, v37, v34
	v_fma_f32 v33, -v33, v36, v35
	v_div_fmas_f32 v33, v33, v34, v36
	v_div_fixup_f32 v32, v33, v32, 1.0
	v_mov_b32_e32 v33, 0
	global_store_dword v33, v32, s[2:3]
.LBB0_135:
	s_or_b64 exec, exec, s[10:11]
	s_waitcnt vmcnt(31)
	v_mul_f32_e32 v32, v29, v29
	v_mul_f32_e32 v33, v31, v31
	v_fmac_f32_e32 v32, v28, v28
	v_fmac_f32_e32 v33, v30, v30
	v_add_f32_e32 v32, v32, v33
	s_waitcnt vmcnt(30)
	v_mul_f32_e32 v33, v25, v25
	v_mul_f32_e32 v34, v27, v27
	v_fmac_f32_e32 v33, v24, v24
	v_fmac_f32_e32 v34, v26, v26
	v_add_f32_e32 v33, v33, v34
	v_add_f32_e32 v32, v32, v33
	s_waitcnt vmcnt(29)
	v_mul_f32_e32 v33, v21, v21
	v_mul_f32_e32 v34, v23, v23
	v_fmac_f32_e32 v33, v20, v20
	v_fmac_f32_e32 v34, v22, v22
	v_add_f32_e32 v33, v33, v34
	v_add_f32_e32 v32, v32, v33
	s_waitcnt vmcnt(28)
	v_mul_f32_e32 v33, v17, v17
	v_mul_f32_e32 v34, v19, v19
	v_fmac_f32_e32 v33, v16, v16
	v_fmac_f32_e32 v34, v18, v18
	v_add_f32_e32 v33, v33, v34
	v_add_f32_e32 v32, v32, v33
	ds_bpermute_b32 v33, v130, v32
	v_bfe_u32 v36, v28, 16, 1
	v_add3_u32 v28, v28, v36, s16
	v_bfe_u32 v36, v29, 16, 1
	v_lshrrev_b32_e32 v28, 16, v28
	s_waitcnt lgkmcnt(0)
	v_add_f32_e32 v32, v32, v33
	ds_bpermute_b32 v33, v131, v32
	v_add3_u32 v29, v29, v36, s16
	s_lshl_b64 s[2:3], s[74:75], 11
	v_and_or_b32 v28, v29, s17, v28
	v_bfe_u32 v29, v30, 16, 1
	s_waitcnt lgkmcnt(0)
	v_add_f32_e32 v32, v32, v33
	s_add_u32 s2, s20, s2
	v_add3_u32 v29, v30, v29, s16
	v_bfe_u32 v30, v31, 16, 1
	ds_bpermute_b32 v33, v132, v32
	s_addc_u32 s3, s21, s3
	v_lshrrev_b32_e32 v29, 16, v29
	v_add3_u32 v30, v31, v30, s16
	v_lshl_add_u64 v[34:35], v[128:129], 3, s[2:3]
	v_and_or_b32 v29, v30, s17, v29
	global_store_dwordx2 v[34:35], v[28:29], off sc1
	v_bfe_u32 v28, v24, 16, 1
	v_add3_u32 v24, v24, v28, s16
	v_bfe_u32 v28, v25, 16, 1
	v_lshrrev_b32_e32 v24, 16, v24
	v_add3_u32 v25, v25, v28, s16
	s_waitcnt lgkmcnt(0)
	v_add_f32_e32 v32, v32, v33
	v_and_or_b32 v24, v25, s17, v24
	v_bfe_u32 v25, v26, 16, 1
	ds_bpermute_b32 v33, v133, v32
	v_add3_u32 v25, v26, v25, s16
	v_bfe_u32 v26, v27, 16, 1
	v_lshrrev_b32_e32 v25, 16, v25
	v_add3_u32 v26, v27, v26, s16
	v_and_or_b32 v25, v26, s17, v25
	global_store_dwordx2 v[34:35], v[24:25], off offset:512 sc1
	v_bfe_u32 v24, v20, 16, 1
	v_add3_u32 v20, v20, v24, s16
	v_bfe_u32 v24, v21, 16, 1
	s_waitcnt lgkmcnt(0)
	v_add_f32_e32 v32, v32, v33
	v_lshrrev_b32_e32 v20, 16, v20
	v_add3_u32 v21, v21, v24, s16
	ds_bpermute_b32 v33, v135, v32
	v_and_or_b32 v20, v21, s17, v20
	v_bfe_u32 v21, v22, 16, 1
	v_add3_u32 v21, v22, v21, s16
	v_bfe_u32 v22, v23, 16, 1
	v_lshrrev_b32_e32 v21, 16, v21
	v_add3_u32 v22, v23, v22, s16
	v_and_or_b32 v21, v22, s17, v21
	global_store_dwordx2 v[34:35], v[20:21], off offset:1024 sc1
	v_bfe_u32 v20, v16, 16, 1
	s_waitcnt lgkmcnt(0)
	v_add_f32_e32 v32, v32, v33
	v_add3_u32 v16, v16, v20, s16
	v_bfe_u32 v20, v17, 16, 1
	ds_bpermute_b32 v33, v134, v32
	v_lshrrev_b32_e32 v16, 16, v16
	v_add3_u32 v17, v17, v20, s16
	v_and_or_b32 v16, v17, s17, v16
	v_bfe_u32 v17, v18, 16, 1
	v_add3_u32 v17, v18, v17, s16
	v_bfe_u32 v18, v19, 16, 1
	v_lshrrev_b32_e32 v17, 16, v17
	v_add3_u32 v18, v19, v18, s16
	v_and_or_b32 v17, v18, s17, v17
	global_store_dwordx2 v[34:35], v[16:17], off offset:1536 sc1
	s_and_saveexec_b64 s[10:11], s[0:1]
	v_readlane_b32 s71, v252, 13
	s_cbranch_execz .LBB0_137
	s_waitcnt lgkmcnt(0)
	v_add_f32_e32 v16, v32, v33
	v_mov_b32_e32 v17, 0x358637bd
	v_fmac_f32_e32 v17, 0x3a800000, v16
	s_mov_b32 s2, 0xf800000
	v_mul_f32_e32 v16, 0x4f800000, v17
	v_cmp_gt_f32_e32 vcc, s2, v17
	s_nop 1
	v_cndmask_b32_e32 v16, v17, v16, vcc
	v_sqrt_f32_e32 v17, v16
	s_nop 0
	v_add_u32_e32 v18, -1, v17
	v_fma_f32 v19, -v18, v17, v16
	v_cmp_ge_f32_e64 s[2:3], 0, v19
	v_add_u32_e32 v19, 1, v17
	s_nop 0
	v_cndmask_b32_e64 v18, v17, v18, s[2:3]
	v_fma_f32 v17, -v19, v17, v16
	v_cmp_lt_f32_e64 s[2:3], 0, v17
	s_nop 1
	v_cndmask_b32_e64 v17, v18, v19, s[2:3]
	v_mul_f32_e32 v18, 0x37800000, v17
	v_cndmask_b32_e32 v17, v17, v18, vcc
	v_mov_b32_e32 v18, 0x260
	v_cmp_class_f32_e32 vcc, v16, v18
	s_nop 1
	v_cndmask_b32_e32 v16, v17, v16, vcc
	v_div_scale_f32 v17, s[2:3], v16, v16, 1.0
	v_rcp_f32_e32 v18, v17
	s_lshl_b64 s[2:3], s[74:75], 2
	s_add_u32 s2, s14, s2
	s_addc_u32 s3, s15, s3
	v_fma_f32 v19, -v17, v18, 1.0
	v_fmac_f32_e32 v18, v19, v18
	v_div_scale_f32 v19, vcc, 1.0, v16, 1.0
	v_mul_f32_e32 v20, v19, v18
	v_fma_f32 v21, -v17, v20, v19
	v_fmac_f32_e32 v20, v21, v18
	v_fma_f32 v17, -v17, v20, v19
	v_div_fmas_f32 v17, v17, v18, v20
	v_div_fixup_f32 v16, v17, v16, 1.0
	v_mov_b32_e32 v17, 0
	global_store_dword v17, v16, s[2:3]
.LBB0_137:
	s_or_b64 exec, exec, s[10:11]
	s_waitcnt vmcnt(31)
	v_mul_f32_e32 v16, v13, v13
	v_mul_f32_e32 v17, v15, v15
	v_fmac_f32_e32 v16, v12, v12
	v_fmac_f32_e32 v17, v14, v14
	v_add_f32_e32 v16, v16, v17
	s_waitcnt vmcnt(30)
	v_mul_f32_e32 v17, v9, v9
	v_mul_f32_e32 v18, v11, v11
	v_fmac_f32_e32 v17, v8, v8
	v_fmac_f32_e32 v18, v10, v10
	v_add_f32_e32 v17, v17, v18
	v_add_f32_e32 v16, v16, v17
	s_waitcnt vmcnt(29)
	v_mul_f32_e32 v17, v5, v5
	v_mul_f32_e32 v18, v7, v7
	v_fmac_f32_e32 v17, v4, v4
	v_fmac_f32_e32 v18, v6, v6
	v_add_f32_e32 v17, v17, v18
	v_add_f32_e32 v16, v16, v17
	s_waitcnt vmcnt(28)
	v_mul_f32_e32 v17, v1, v1
	v_mul_f32_e32 v18, v3, v3
	v_fmac_f32_e32 v17, v0, v0
	v_fmac_f32_e32 v18, v2, v2
	v_add_f32_e32 v17, v17, v18
	v_add_f32_e32 v16, v16, v17
	ds_bpermute_b32 v17, v130, v16
	v_bfe_u32 v20, v12, 16, 1
	v_add3_u32 v12, v12, v20, s16
	v_bfe_u32 v20, v13, 16, 1
	v_lshrrev_b32_e32 v12, 16, v12
	s_waitcnt lgkmcnt(0)
	v_add_f32_e32 v16, v16, v17
	ds_bpermute_b32 v17, v131, v16
	v_add3_u32 v13, v13, v20, s16
	s_lshl_b64 s[2:3], s[72:73], 11
	v_and_or_b32 v12, v13, s17, v12
	v_bfe_u32 v13, v14, 16, 1
	s_waitcnt lgkmcnt(0)
	v_add_f32_e32 v16, v16, v17
	s_add_u32 s2, s20, s2
	v_add3_u32 v13, v14, v13, s16
	v_bfe_u32 v14, v15, 16, 1
	ds_bpermute_b32 v17, v132, v16
	s_addc_u32 s3, s21, s3
	v_lshrrev_b32_e32 v13, 16, v13
	v_add3_u32 v14, v15, v14, s16
	v_lshl_add_u64 v[18:19], v[128:129], 3, s[2:3]
	v_and_or_b32 v13, v14, s17, v13
	global_store_dwordx2 v[18:19], v[12:13], off sc1
	v_bfe_u32 v12, v8, 16, 1
	v_add3_u32 v8, v8, v12, s16
	v_bfe_u32 v12, v9, 16, 1
	v_lshrrev_b32_e32 v8, 16, v8
	v_add3_u32 v9, v9, v12, s16
	s_waitcnt lgkmcnt(0)
	v_add_f32_e32 v16, v16, v17
	v_and_or_b32 v8, v9, s17, v8
	v_bfe_u32 v9, v10, 16, 1
	ds_bpermute_b32 v17, v133, v16
	v_add3_u32 v9, v10, v9, s16
	v_bfe_u32 v10, v11, 16, 1
	v_lshrrev_b32_e32 v9, 16, v9
	v_add3_u32 v10, v11, v10, s16
	v_and_or_b32 v9, v10, s17, v9
	global_store_dwordx2 v[18:19], v[8:9], off offset:512 sc1
	v_bfe_u32 v8, v4, 16, 1
	v_add3_u32 v4, v4, v8, s16
	v_bfe_u32 v8, v5, 16, 1
	s_waitcnt lgkmcnt(0)
	v_add_f32_e32 v16, v16, v17
	v_lshrrev_b32_e32 v4, 16, v4
	v_add3_u32 v5, v5, v8, s16
	ds_bpermute_b32 v17, v135, v16
	v_and_or_b32 v4, v5, s17, v4
	v_bfe_u32 v5, v6, 16, 1
	v_add3_u32 v5, v6, v5, s16
	v_bfe_u32 v6, v7, 16, 1
	v_lshrrev_b32_e32 v5, 16, v5
	v_add3_u32 v6, v7, v6, s16
	v_and_or_b32 v5, v6, s17, v5
	global_store_dwordx2 v[18:19], v[4:5], off offset:1024 sc1
	v_bfe_u32 v4, v0, 16, 1
	s_waitcnt lgkmcnt(0)
	v_add_f32_e32 v16, v16, v17
	v_add3_u32 v0, v0, v4, s16
	v_bfe_u32 v4, v1, 16, 1
	ds_bpermute_b32 v17, v134, v16
	v_lshrrev_b32_e32 v0, 16, v0
	v_add3_u32 v1, v1, v4, s16
	v_and_or_b32 v0, v1, s17, v0
	v_bfe_u32 v1, v2, 16, 1
	v_add3_u32 v1, v2, v1, s16
	v_bfe_u32 v2, v3, 16, 1
	v_lshrrev_b32_e32 v1, 16, v1
	v_add3_u32 v2, v3, v2, s16
	v_and_or_b32 v1, v2, s17, v1
	global_store_dwordx2 v[18:19], v[0:1], off offset:1536 sc1
	s_and_saveexec_b64 s[10:11], s[0:1]
	s_cbranch_execz .LBB0_139
	s_waitcnt lgkmcnt(0)
	v_add_f32_e32 v0, v16, v17
	v_mov_b32_e32 v1, 0x358637bd
	v_fmac_f32_e32 v1, 0x3a800000, v0
	s_mov_b32 s2, 0xf800000
	v_mul_f32_e32 v0, 0x4f800000, v1
	v_cmp_gt_f32_e32 vcc, s2, v1
	s_nop 1
	v_cndmask_b32_e32 v0, v1, v0, vcc
	v_sqrt_f32_e32 v1, v0
	s_nop 0
	v_add_u32_e32 v2, -1, v1
	v_fma_f32 v3, -v2, v1, v0
	v_cmp_ge_f32_e64 s[2:3], 0, v3
	v_add_u32_e32 v3, 1, v1
	s_nop 0
	v_cndmask_b32_e64 v2, v1, v2, s[2:3]
	v_fma_f32 v1, -v3, v1, v0
	v_cmp_lt_f32_e64 s[2:3], 0, v1
	s_nop 1
	v_cndmask_b32_e64 v1, v2, v3, s[2:3]
	v_mul_f32_e32 v2, 0x37800000, v1
	v_cndmask_b32_e32 v1, v1, v2, vcc
	v_mov_b32_e32 v2, 0x260
	v_cmp_class_f32_e32 vcc, v0, v2
	s_nop 1
	v_cndmask_b32_e32 v0, v1, v0, vcc
	v_div_scale_f32 v1, s[2:3], v0, v0, 1.0
	v_rcp_f32_e32 v2, v1
	s_lshl_b64 s[2:3], s[72:73], 2
	s_add_u32 s2, s14, s2
	s_addc_u32 s3, s15, s3
	v_fma_f32 v3, -v1, v2, 1.0
	v_fmac_f32_e32 v2, v3, v2
	v_div_scale_f32 v3, vcc, 1.0, v0, 1.0
	v_mul_f32_e32 v4, v3, v2
	v_fma_f32 v5, -v1, v4, v3
	v_fmac_f32_e32 v4, v5, v2
	v_fma_f32 v1, -v1, v4, v3
	v_div_fmas_f32 v1, v1, v2, v4
	v_div_fixup_f32 v0, v1, v0, 1.0
	v_mov_b32_e32 v1, 0
	global_store_dword v1, v0, s[2:3]
.LBB0_139:
	s_or_b64 exec, exec, s[10:11]
	s_waitcnt vmcnt(31)
	v_mul_f32_e32 v0, v125, v125
	v_mul_f32_e32 v1, v127, v127
	v_fmac_f32_e32 v0, v124, v124
	v_fmac_f32_e32 v1, v126, v126
	v_add_f32_e32 v0, v0, v1
	s_waitcnt vmcnt(30)
	v_mul_f32_e32 v1, v121, v121
	v_mul_f32_e32 v2, v123, v123
	v_fmac_f32_e32 v1, v120, v120
	v_fmac_f32_e32 v2, v122, v122
	v_add_f32_e32 v1, v1, v2
	v_add_f32_e32 v0, v0, v1
	s_waitcnt vmcnt(29)
	v_mul_f32_e32 v1, v117, v117
	v_mul_f32_e32 v2, v119, v119
	v_fmac_f32_e32 v1, v116, v116
	v_fmac_f32_e32 v2, v118, v118
	v_add_f32_e32 v1, v1, v2
	v_add_f32_e32 v0, v0, v1
	s_waitcnt vmcnt(28)
	v_mul_f32_e32 v1, v113, v113
	v_mul_f32_e32 v2, v115, v115
	v_fmac_f32_e32 v1, v112, v112
	v_fmac_f32_e32 v2, v114, v114
	v_add_f32_e32 v1, v1, v2
	v_add_f32_e32 v0, v0, v1
	ds_bpermute_b32 v1, v130, v0
	v_bfe_u32 v4, v124, 16, 1
	v_add3_u32 v4, v124, v4, s16
	v_bfe_u32 v5, v125, 16, 1
	v_lshrrev_b32_e32 v4, 16, v4
	s_waitcnt lgkmcnt(0)
	v_add_f32_e32 v0, v0, v1
	ds_bpermute_b32 v1, v131, v0
	v_add3_u32 v5, v125, v5, s16
	s_lshl_b64 s[2:3], s[6:7], 11
	v_and_or_b32 v4, v5, s17, v4
	v_bfe_u32 v5, v126, 16, 1
	s_waitcnt lgkmcnt(0)
	v_add_f32_e32 v0, v0, v1
	s_add_u32 s2, s20, s2
	v_add3_u32 v5, v126, v5, s16
	v_bfe_u32 v6, v127, 16, 1
	ds_bpermute_b32 v1, v132, v0
	s_addc_u32 s3, s21, s3
	v_lshrrev_b32_e32 v5, 16, v5
	v_add3_u32 v6, v127, v6, s16
	v_lshl_add_u64 v[2:3], v[128:129], 3, s[2:3]
	v_and_or_b32 v5, v6, s17, v5
	global_store_dwordx2 v[2:3], v[4:5], off sc1
	v_bfe_u32 v4, v120, 16, 1
	v_add3_u32 v4, v120, v4, s16
	v_bfe_u32 v5, v121, 16, 1
	v_lshrrev_b32_e32 v4, 16, v4
	v_add3_u32 v5, v121, v5, s16
	s_waitcnt lgkmcnt(0)
	v_add_f32_e32 v0, v0, v1
	v_and_or_b32 v4, v5, s17, v4
	v_bfe_u32 v5, v122, 16, 1
	ds_bpermute_b32 v1, v133, v0
	v_add3_u32 v5, v122, v5, s16
	v_bfe_u32 v6, v123, 16, 1
	v_lshrrev_b32_e32 v5, 16, v5
	v_add3_u32 v6, v123, v6, s16
	v_and_or_b32 v5, v6, s17, v5
	global_store_dwordx2 v[2:3], v[4:5], off offset:512 sc1
	v_bfe_u32 v4, v116, 16, 1
	v_add3_u32 v4, v116, v4, s16
	v_bfe_u32 v5, v117, 16, 1
	s_waitcnt lgkmcnt(0)
	v_add_f32_e32 v0, v0, v1
	v_lshrrev_b32_e32 v4, 16, v4
	v_add3_u32 v5, v117, v5, s16
	ds_bpermute_b32 v1, v135, v0
	v_and_or_b32 v4, v5, s17, v4
	v_bfe_u32 v5, v118, 16, 1
	v_add3_u32 v5, v118, v5, s16
	v_bfe_u32 v6, v119, 16, 1
	v_lshrrev_b32_e32 v5, 16, v5
	v_add3_u32 v6, v119, v6, s16
	v_and_or_b32 v5, v6, s17, v5
	global_store_dwordx2 v[2:3], v[4:5], off offset:1024 sc1
	v_bfe_u32 v4, v112, 16, 1
	s_waitcnt lgkmcnt(0)
	v_add_f32_e32 v0, v0, v1
	v_add3_u32 v4, v112, v4, s16
	v_bfe_u32 v5, v113, 16, 1
	ds_bpermute_b32 v1, v134, v0
	v_lshrrev_b32_e32 v4, 16, v4
	v_add3_u32 v5, v113, v5, s16
	v_and_or_b32 v4, v5, s17, v4
	v_bfe_u32 v5, v114, 16, 1
	v_add3_u32 v5, v114, v5, s16
	v_bfe_u32 v6, v115, 16, 1
	v_lshrrev_b32_e32 v5, 16, v5
	v_add3_u32 v6, v115, v6, s16
	v_and_or_b32 v5, v6, s17, v5
	global_store_dwordx2 v[2:3], v[4:5], off offset:1536 sc1
	s_and_saveexec_b64 s[10:11], s[0:1]
	s_cbranch_execz .LBB0_141
	s_waitcnt lgkmcnt(0)
	v_add_f32_e32 v0, v0, v1
	v_mov_b32_e32 v1, 0x358637bd
	v_fmac_f32_e32 v1, 0x3a800000, v0
	s_mov_b32 s2, 0xf800000
	v_mul_f32_e32 v0, 0x4f800000, v1
	v_cmp_gt_f32_e32 vcc, s2, v1
	s_nop 1
	v_cndmask_b32_e32 v0, v1, v0, vcc
	v_sqrt_f32_e32 v1, v0
	s_nop 0
	v_add_u32_e32 v2, -1, v1
	v_fma_f32 v3, -v2, v1, v0
	v_cmp_ge_f32_e64 s[2:3], 0, v3
	v_add_u32_e32 v3, 1, v1
	s_nop 0
	v_cndmask_b32_e64 v2, v1, v2, s[2:3]
	v_fma_f32 v1, -v3, v1, v0
	v_cmp_lt_f32_e64 s[2:3], 0, v1
	s_nop 1
	v_cndmask_b32_e64 v1, v2, v3, s[2:3]
	v_mul_f32_e32 v2, 0x37800000, v1
	v_cndmask_b32_e32 v1, v1, v2, vcc
	v_mov_b32_e32 v2, 0x260
	v_cmp_class_f32_e32 vcc, v0, v2
	s_nop 1
	v_cndmask_b32_e32 v0, v1, v0, vcc
	v_div_scale_f32 v1, s[2:3], v0, v0, 1.0
	v_rcp_f32_e32 v2, v1
	s_lshl_b64 s[2:3], s[6:7], 2
	s_add_u32 s2, s14, s2
	s_addc_u32 s3, s15, s3
	v_fma_f32 v3, -v1, v2, 1.0
	v_fmac_f32_e32 v2, v3, v2
	v_div_scale_f32 v3, vcc, 1.0, v0, 1.0
	v_mul_f32_e32 v4, v3, v2
	v_fma_f32 v5, -v1, v4, v3
	v_fmac_f32_e32 v4, v5, v2
	v_fma_f32 v1, -v1, v4, v3
	v_div_fmas_f32 v1, v1, v2, v4
	v_div_fixup_f32 v0, v1, v0, 1.0
	v_mov_b32_e32 v1, 0
	global_store_dword v1, v0, s[2:3]
.LBB0_141:
	s_or_b64 exec, exec, s[10:11]
	s_waitcnt vmcnt(31)
	v_mul_f32_e32 v0, v109, v109
	s_waitcnt lgkmcnt(0)
	v_mul_f32_e32 v1, v111, v111
	v_fmac_f32_e32 v0, v108, v108
	v_fmac_f32_e32 v1, v110, v110
	v_add_f32_e32 v0, v0, v1
	s_waitcnt vmcnt(30)
	v_mul_f32_e32 v1, v105, v105
	v_mul_f32_e32 v2, v107, v107
	v_fmac_f32_e32 v1, v104, v104
	v_fmac_f32_e32 v2, v106, v106
	v_add_f32_e32 v1, v1, v2
	v_add_f32_e32 v0, v0, v1
	s_waitcnt vmcnt(29)
	v_mul_f32_e32 v1, v101, v101
	v_mul_f32_e32 v2, v103, v103
	v_fmac_f32_e32 v1, v100, v100
	v_fmac_f32_e32 v2, v102, v102
	v_add_f32_e32 v1, v1, v2
	v_add_f32_e32 v0, v0, v1
	s_waitcnt vmcnt(28)
	v_mul_f32_e32 v1, v97, v97
	v_mul_f32_e32 v2, v99, v99
	v_fmac_f32_e32 v1, v96, v96
	v_fmac_f32_e32 v2, v98, v98
	v_add_f32_e32 v1, v1, v2
	v_add_f32_e32 v0, v0, v1
	ds_bpermute_b32 v1, v130, v0
	v_bfe_u32 v4, v108, 16, 1
	v_add3_u32 v4, v108, v4, s16
	v_bfe_u32 v5, v109, 16, 1
	v_lshrrev_b32_e32 v4, 16, v4
	s_waitcnt lgkmcnt(0)
	v_add_f32_e32 v0, v0, v1
	ds_bpermute_b32 v1, v131, v0
	v_add3_u32 v5, v109, v5, s16
	s_lshl_b64 s[2:3], s[8:9], 11
	v_and_or_b32 v4, v5, s17, v4
	v_bfe_u32 v5, v110, 16, 1
	s_waitcnt lgkmcnt(0)
	v_add_f32_e32 v0, v0, v1
	s_add_u32 s2, s20, s2
	v_add3_u32 v5, v110, v5, s16
	v_bfe_u32 v6, v111, 16, 1
	ds_bpermute_b32 v1, v132, v0
	s_addc_u32 s3, s21, s3
	v_lshrrev_b32_e32 v5, 16, v5
	v_add3_u32 v6, v111, v6, s16
	v_lshl_add_u64 v[2:3], v[128:129], 3, s[2:3]
	v_and_or_b32 v5, v6, s17, v5
	global_store_dwordx2 v[2:3], v[4:5], off sc1
	v_bfe_u32 v4, v104, 16, 1
	v_add3_u32 v4, v104, v4, s16
	v_bfe_u32 v5, v105, 16, 1
	v_lshrrev_b32_e32 v4, 16, v4
	v_add3_u32 v5, v105, v5, s16
	s_waitcnt lgkmcnt(0)
	v_add_f32_e32 v0, v0, v1
	v_and_or_b32 v4, v5, s17, v4
	v_bfe_u32 v5, v106, 16, 1
	ds_bpermute_b32 v1, v133, v0
	v_add3_u32 v5, v106, v5, s16
	v_bfe_u32 v6, v107, 16, 1
	v_lshrrev_b32_e32 v5, 16, v5
	v_add3_u32 v6, v107, v6, s16
	v_and_or_b32 v5, v6, s17, v5
	global_store_dwordx2 v[2:3], v[4:5], off offset:512 sc1
	v_bfe_u32 v4, v100, 16, 1
	v_add3_u32 v4, v100, v4, s16
	v_bfe_u32 v5, v101, 16, 1
	s_waitcnt lgkmcnt(0)
	v_add_f32_e32 v0, v0, v1
	v_lshrrev_b32_e32 v4, 16, v4
	v_add3_u32 v5, v101, v5, s16
	ds_bpermute_b32 v1, v135, v0
	v_and_or_b32 v4, v5, s17, v4
	v_bfe_u32 v5, v102, 16, 1
	v_add3_u32 v5, v102, v5, s16
	v_bfe_u32 v6, v103, 16, 1
	v_lshrrev_b32_e32 v5, 16, v5
	v_add3_u32 v6, v103, v6, s16
	v_and_or_b32 v5, v6, s17, v5
	global_store_dwordx2 v[2:3], v[4:5], off offset:1024 sc1
	v_bfe_u32 v4, v96, 16, 1
	s_waitcnt lgkmcnt(0)
	v_add_f32_e32 v0, v0, v1
	v_add3_u32 v4, v96, v4, s16
	v_bfe_u32 v5, v97, 16, 1
	ds_bpermute_b32 v1, v134, v0
	v_lshrrev_b32_e32 v4, 16, v4
	v_add3_u32 v5, v97, v5, s16
	v_and_or_b32 v4, v5, s17, v4
	v_bfe_u32 v5, v98, 16, 1
	v_add3_u32 v5, v98, v5, s16
	v_bfe_u32 v6, v99, 16, 1
	v_lshrrev_b32_e32 v5, 16, v5
	v_add3_u32 v6, v99, v6, s16
	v_and_or_b32 v5, v6, s17, v5
	global_store_dwordx2 v[2:3], v[4:5], off offset:1536 sc1
	s_and_saveexec_b64 s[10:11], s[0:1]
	s_cbranch_execz .LBB0_143
	s_waitcnt lgkmcnt(0)
	v_add_f32_e32 v0, v0, v1
	v_mov_b32_e32 v1, 0x358637bd
	v_fmac_f32_e32 v1, 0x3a800000, v0
	s_mov_b32 s2, 0xf800000
	v_mul_f32_e32 v0, 0x4f800000, v1
	v_cmp_gt_f32_e32 vcc, s2, v1
	s_nop 1
	v_cndmask_b32_e32 v0, v1, v0, vcc
	v_sqrt_f32_e32 v1, v0
	s_nop 0
	v_add_u32_e32 v2, -1, v1
	v_fma_f32 v3, -v2, v1, v0
	v_cmp_ge_f32_e64 s[2:3], 0, v3
	v_add_u32_e32 v3, 1, v1
	s_nop 0
	v_cndmask_b32_e64 v2, v1, v2, s[2:3]
	v_fma_f32 v1, -v3, v1, v0
	v_cmp_lt_f32_e64 s[2:3], 0, v1
	s_nop 1
	v_cndmask_b32_e64 v1, v2, v3, s[2:3]
	v_mul_f32_e32 v2, 0x37800000, v1
	v_cndmask_b32_e32 v1, v1, v2, vcc
	v_mov_b32_e32 v2, 0x260
	v_cmp_class_f32_e32 vcc, v0, v2
	s_nop 1
	v_cndmask_b32_e32 v0, v1, v0, vcc
	v_div_scale_f32 v1, s[2:3], v0, v0, 1.0
	v_rcp_f32_e32 v2, v1
	s_lshl_b64 s[2:3], s[8:9], 2
	s_add_u32 s2, s14, s2
	s_addc_u32 s3, s15, s3
	v_fma_f32 v3, -v1, v2, 1.0
	v_fmac_f32_e32 v2, v3, v2
	v_div_scale_f32 v3, vcc, 1.0, v0, 1.0
	v_mul_f32_e32 v4, v3, v2
	v_fma_f32 v5, -v1, v4, v3
	v_fmac_f32_e32 v4, v5, v2
	v_fma_f32 v1, -v1, v4, v3
	v_div_fmas_f32 v1, v1, v2, v4
	v_div_fixup_f32 v0, v1, v0, 1.0
	v_mov_b32_e32 v1, 0
	global_store_dword v1, v0, s[2:3]
.LBB0_143:
	s_or_b64 exec, exec, s[10:11]
	s_waitcnt vmcnt(31)
	v_mul_f32_e32 v0, v93, v93
	s_waitcnt lgkmcnt(0)
	v_mul_f32_e32 v1, v95, v95
	v_fmac_f32_e32 v0, v92, v92
	v_fmac_f32_e32 v1, v94, v94
	v_add_f32_e32 v0, v0, v1
	s_waitcnt vmcnt(30)
	v_mul_f32_e32 v1, v89, v89
	v_mul_f32_e32 v2, v91, v91
	v_fmac_f32_e32 v1, v88, v88
	v_fmac_f32_e32 v2, v90, v90
	v_add_f32_e32 v1, v1, v2
	v_add_f32_e32 v0, v0, v1
	s_waitcnt vmcnt(29)
	v_mul_f32_e32 v1, v85, v85
	v_mul_f32_e32 v2, v87, v87
	v_fmac_f32_e32 v1, v84, v84
	v_fmac_f32_e32 v2, v86, v86
	v_add_f32_e32 v1, v1, v2
	v_add_f32_e32 v0, v0, v1
	s_waitcnt vmcnt(28)
	v_mul_f32_e32 v1, v81, v81
	v_mul_f32_e32 v2, v83, v83
	v_fmac_f32_e32 v1, v80, v80
	v_fmac_f32_e32 v2, v82, v82
	v_add_f32_e32 v1, v1, v2
	v_add_f32_e32 v0, v0, v1
	ds_bpermute_b32 v1, v130, v0
	v_bfe_u32 v4, v92, 16, 1
	s_movk_i32 s7, 0x7fff
	s_add_i32 s8, s6, s13
	v_add3_u32 v4, v92, v4, s7
	s_waitcnt lgkmcnt(0)
	v_add_f32_e32 v0, v0, v1
	ds_bpermute_b32 v1, v131, v0
	v_bfe_u32 v5, v93, 16, 1
	s_ashr_i32 s9, s8, 31
	v_lshrrev_b32_e32 v4, 16, v4
	v_add3_u32 v5, v93, v5, s7
	s_mov_b32 s13, 0xffff0000
	s_lshl_b64 s[2:3], s[8:9], 11
	v_and_or_b32 v4, v5, s13, v4
	v_bfe_u32 v5, v94, 16, 1
	s_waitcnt lgkmcnt(0)
	v_add_f32_e32 v0, v0, v1
	s_add_u32 s2, s20, s2
	v_add3_u32 v5, v94, v5, s7
	v_bfe_u32 v6, v95, 16, 1
	ds_bpermute_b32 v1, v132, v0
	s_addc_u32 s3, s21, s3
	v_lshrrev_b32_e32 v5, 16, v5
	v_add3_u32 v6, v95, v6, s7
	v_lshl_add_u64 v[2:3], v[128:129], 3, s[2:3]
	v_and_or_b32 v5, v6, s13, v5
	global_store_dwordx2 v[2:3], v[4:5], off sc1
	v_bfe_u32 v4, v88, 16, 1
	v_add3_u32 v4, v88, v4, s7
	v_bfe_u32 v5, v89, 16, 1
	v_lshrrev_b32_e32 v4, 16, v4
	v_add3_u32 v5, v89, v5, s7
	s_waitcnt lgkmcnt(0)
	v_add_f32_e32 v0, v0, v1
	v_and_or_b32 v4, v5, s13, v4
	v_bfe_u32 v5, v90, 16, 1
	ds_bpermute_b32 v1, v133, v0
	v_add3_u32 v5, v90, v5, s7
	v_bfe_u32 v6, v91, 16, 1
	v_lshrrev_b32_e32 v5, 16, v5
	v_add3_u32 v6, v91, v6, s7
	v_and_or_b32 v5, v6, s13, v5
	global_store_dwordx2 v[2:3], v[4:5], off offset:512 sc1
	v_bfe_u32 v4, v84, 16, 1
	v_add3_u32 v4, v84, v4, s7
	v_bfe_u32 v5, v85, 16, 1
	s_waitcnt lgkmcnt(0)
	v_add_f32_e32 v0, v0, v1
	v_lshrrev_b32_e32 v4, 16, v4
	v_add3_u32 v5, v85, v5, s7
	ds_bpermute_b32 v1, v135, v0
	v_and_or_b32 v4, v5, s13, v4
	v_bfe_u32 v5, v86, 16, 1
	v_add3_u32 v5, v86, v5, s7
	v_bfe_u32 v6, v87, 16, 1
	v_lshrrev_b32_e32 v5, 16, v5
	v_add3_u32 v6, v87, v6, s7
	v_and_or_b32 v5, v6, s13, v5
	global_store_dwordx2 v[2:3], v[4:5], off offset:1024 sc1
	v_bfe_u32 v4, v80, 16, 1
	s_waitcnt lgkmcnt(0)
	v_add_f32_e32 v0, v0, v1
	v_add3_u32 v4, v80, v4, s7
	v_bfe_u32 v5, v81, 16, 1
	ds_bpermute_b32 v1, v134, v0
	v_lshrrev_b32_e32 v4, 16, v4
	v_add3_u32 v5, v81, v5, s7
	v_and_or_b32 v4, v5, s13, v4
	v_bfe_u32 v5, v82, 16, 1
	v_add3_u32 v5, v82, v5, s7
	v_bfe_u32 v6, v83, 16, 1
	v_lshrrev_b32_e32 v5, 16, v5
	v_add3_u32 v6, v83, v6, s7
	v_and_or_b32 v5, v6, s13, v5
	global_store_dwordx2 v[2:3], v[4:5], off offset:1536 sc1
	s_and_saveexec_b64 s[10:11], s[0:1]
	s_cbranch_execz .LBB0_145
	s_waitcnt lgkmcnt(0)
	v_add_f32_e32 v0, v0, v1
	v_mov_b32_e32 v1, 0x358637bd
	v_fmac_f32_e32 v1, 0x3a800000, v0
	s_mov_b32 s2, 0xf800000
	v_mul_f32_e32 v0, 0x4f800000, v1
	v_cmp_gt_f32_e32 vcc, s2, v1
	s_nop 1
	v_cndmask_b32_e32 v0, v1, v0, vcc
	v_sqrt_f32_e32 v1, v0
	s_nop 0
	v_add_u32_e32 v2, -1, v1
	v_fma_f32 v3, -v2, v1, v0
	v_cmp_ge_f32_e64 s[2:3], 0, v3
	v_add_u32_e32 v3, 1, v1
	s_nop 0
	v_cndmask_b32_e64 v2, v1, v2, s[2:3]
	v_fma_f32 v1, -v3, v1, v0
	v_cmp_lt_f32_e64 s[2:3], 0, v1
	s_nop 1
	v_cndmask_b32_e64 v1, v2, v3, s[2:3]
	v_mul_f32_e32 v2, 0x37800000, v1
	v_cndmask_b32_e32 v1, v1, v2, vcc
	v_mov_b32_e32 v2, 0x260
	v_cmp_class_f32_e32 vcc, v0, v2
	s_nop 1
	v_cndmask_b32_e32 v0, v1, v0, vcc
	v_div_scale_f32 v1, s[2:3], v0, v0, 1.0
	v_rcp_f32_e32 v2, v1
	s_lshl_b64 s[2:3], s[8:9], 2
	s_add_u32 s2, s14, s2
	s_addc_u32 s3, s15, s3
	v_fma_f32 v3, -v1, v2, 1.0
	v_fmac_f32_e32 v2, v3, v2
	v_div_scale_f32 v3, vcc, 1.0, v0, 1.0
	v_mul_f32_e32 v4, v3, v2
	v_fma_f32 v5, -v1, v4, v3
	v_fmac_f32_e32 v4, v5, v2
	v_fma_f32 v1, -v1, v4, v3
	v_div_fmas_f32 v1, v1, v2, v4
	v_div_fixup_f32 v0, v1, v0, 1.0
	v_mov_b32_e32 v1, 0
	global_store_dword v1, v0, s[2:3]
.LBB0_145:
	s_or_b64 exec, exec, s[10:11]
	s_waitcnt vmcnt(31)
	v_mul_f32_e32 v0, v77, v77
	s_waitcnt lgkmcnt(0)
	v_mul_f32_e32 v1, v79, v79
	v_fmac_f32_e32 v0, v76, v76
	v_fmac_f32_e32 v1, v78, v78
	v_add_f32_e32 v0, v0, v1
	s_waitcnt vmcnt(30)
	v_mul_f32_e32 v1, v73, v73
	v_mul_f32_e32 v2, v75, v75
	v_fmac_f32_e32 v1, v72, v72
	v_fmac_f32_e32 v2, v74, v74
	v_add_f32_e32 v1, v1, v2
	v_add_f32_e32 v0, v0, v1
	s_waitcnt vmcnt(29)
	v_mul_f32_e32 v1, v69, v69
	v_mul_f32_e32 v2, v71, v71
	v_fmac_f32_e32 v1, v68, v68
	v_fmac_f32_e32 v2, v70, v70
	v_add_f32_e32 v1, v1, v2
	v_add_f32_e32 v0, v0, v1
	s_waitcnt vmcnt(28)
	v_mul_f32_e32 v1, v65, v65
	v_mul_f32_e32 v2, v67, v67
	v_fmac_f32_e32 v1, v64, v64
	v_fmac_f32_e32 v2, v66, v66
	v_add_f32_e32 v1, v1, v2
	v_add_f32_e32 v0, v0, v1
	ds_bpermute_b32 v1, v130, v0
	v_bfe_u32 v4, v76, 16, 1
	s_add_i32 s2, s6, s12
	v_add3_u32 v4, v76, v4, s7
	v_bfe_u32 v5, v77, 16, 1
	s_waitcnt lgkmcnt(0)
	v_add_f32_e32 v0, v0, v1
	ds_bpermute_b32 v1, v131, v0
	s_ashr_i32 s3, s2, 31
	v_lshrrev_b32_e32 v4, 16, v4
	v_add3_u32 v5, v77, v5, s7
	s_lshl_b64 s[8:9], s[2:3], 11
	v_and_or_b32 v4, v5, s13, v4
	v_bfe_u32 v5, v78, 16, 1
	s_waitcnt lgkmcnt(0)
	v_add_f32_e32 v0, v0, v1
	s_add_u32 s8, s20, s8
	v_add3_u32 v5, v78, v5, s7
	v_bfe_u32 v6, v79, 16, 1
	ds_bpermute_b32 v1, v132, v0
	s_addc_u32 s9, s21, s9
	v_lshrrev_b32_e32 v5, 16, v5
	v_add3_u32 v6, v79, v6, s7
	v_lshl_add_u64 v[2:3], v[128:129], 3, s[8:9]
	v_and_or_b32 v5, v6, s13, v5
	global_store_dwordx2 v[2:3], v[4:5], off sc1
	v_bfe_u32 v4, v72, 16, 1
	v_add3_u32 v4, v72, v4, s7
	v_bfe_u32 v5, v73, 16, 1
	v_lshrrev_b32_e32 v4, 16, v4
	v_add3_u32 v5, v73, v5, s7
	s_waitcnt lgkmcnt(0)
	v_add_f32_e32 v0, v0, v1
	v_and_or_b32 v4, v5, s13, v4
	v_bfe_u32 v5, v74, 16, 1
	ds_bpermute_b32 v1, v133, v0
	v_add3_u32 v5, v74, v5, s7
	v_bfe_u32 v6, v75, 16, 1
	v_lshrrev_b32_e32 v5, 16, v5
	v_add3_u32 v6, v75, v6, s7
	v_and_or_b32 v5, v6, s13, v5
	global_store_dwordx2 v[2:3], v[4:5], off offset:512 sc1
	v_bfe_u32 v4, v68, 16, 1
	v_add3_u32 v4, v68, v4, s7
	v_bfe_u32 v5, v69, 16, 1
	s_waitcnt lgkmcnt(0)
	v_add_f32_e32 v0, v0, v1
	v_lshrrev_b32_e32 v4, 16, v4
	v_add3_u32 v5, v69, v5, s7
	ds_bpermute_b32 v1, v135, v0
	v_and_or_b32 v4, v5, s13, v4
	v_bfe_u32 v5, v70, 16, 1
	v_add3_u32 v5, v70, v5, s7
	v_bfe_u32 v6, v71, 16, 1
	v_lshrrev_b32_e32 v5, 16, v5
	v_add3_u32 v6, v71, v6, s7
	v_and_or_b32 v5, v6, s13, v5
	global_store_dwordx2 v[2:3], v[4:5], off offset:1024 sc1
	v_bfe_u32 v4, v64, 16, 1
	s_waitcnt lgkmcnt(0)
	v_add_f32_e32 v0, v0, v1
	v_add3_u32 v4, v64, v4, s7
	v_bfe_u32 v5, v65, 16, 1
	ds_bpermute_b32 v1, v134, v0
	v_lshrrev_b32_e32 v4, 16, v4
	v_add3_u32 v5, v65, v5, s7
	v_and_or_b32 v4, v5, s13, v4
	v_bfe_u32 v5, v66, 16, 1
	v_add3_u32 v5, v66, v5, s7
	v_bfe_u32 v6, v67, 16, 1
	v_lshrrev_b32_e32 v5, 16, v5
	v_add3_u32 v6, v67, v6, s7
	v_and_or_b32 v5, v6, s13, v5
	global_store_dwordx2 v[2:3], v[4:5], off offset:1536 sc1
	s_and_saveexec_b64 s[6:7], s[0:1]
	s_cbranch_execz .LBB0_147
	s_waitcnt lgkmcnt(0)
	v_add_f32_e32 v0, v0, v1
	v_mov_b32_e32 v1, 0x358637bd
	v_fmac_f32_e32 v1, 0x3a800000, v0
	s_mov_b32 s0, 0xf800000
	v_mul_f32_e32 v0, 0x4f800000, v1
	v_cmp_gt_f32_e32 vcc, s0, v1
	s_nop 1
	v_cndmask_b32_e32 v0, v1, v0, vcc
	v_sqrt_f32_e32 v1, v0
	s_nop 0
	v_add_u32_e32 v2, -1, v1
	v_fma_f32 v3, -v2, v1, v0
	v_cmp_ge_f32_e64 s[0:1], 0, v3
	v_add_u32_e32 v3, 1, v1
	s_nop 0
	v_cndmask_b32_e64 v2, v1, v2, s[0:1]
	v_fma_f32 v1, -v3, v1, v0
	v_cmp_lt_f32_e64 s[0:1], 0, v1
	s_nop 1
	v_cndmask_b32_e64 v1, v2, v3, s[0:1]
	v_mul_f32_e32 v2, 0x37800000, v1
	v_cndmask_b32_e32 v1, v1, v2, vcc
	v_mov_b32_e32 v2, 0x260
	v_cmp_class_f32_e32 vcc, v0, v2
	s_nop 1
	v_cndmask_b32_e32 v0, v1, v0, vcc
	v_div_scale_f32 v1, s[0:1], v0, v0, 1.0
	v_rcp_f32_e32 v2, v1
	s_lshl_b64 s[0:1], s[2:3], 2
	s_add_u32 s0, s14, s0
	s_addc_u32 s1, s15, s1
	v_fma_f32 v3, -v1, v2, 1.0
	v_fmac_f32_e32 v2, v3, v2
	v_div_scale_f32 v3, vcc, 1.0, v0, 1.0
	v_mul_f32_e32 v4, v3, v2
	v_fma_f32 v5, -v1, v4, v3
	v_fmac_f32_e32 v4, v5, v2
	v_fma_f32 v1, -v1, v4, v3
	v_div_fmas_f32 v1, v1, v2, v4
	v_div_fixup_f32 v0, v1, v0, 1.0
	v_mov_b32_e32 v1, 0
	global_store_dword v1, v0, s[0:1]
